# qkv unit: coalesced A-fragment loads (4 lanes per row) + per-wave LDS transpose into MFMA layout
# speedup vs baseline: 1.0248x; 1.0091x over previous
; #define LAS __attribute__((address_space(3)))
; __device__ __forceinline__ void qkv_head_unit(const Params& p, LAS unsigned char* lds, int h, int blk_begin, int blk_end) {
;     ...
;     float frq[4];
; #pragma unroll
;     for (int i = 0; i < 4; ++i) frq[i] = exp2f(-(float)(4 * fq + i) * (13.287712379549449f / 16.0f));
;     __syncthreads();
;     { const bf16_t* W = (const bf16_t*)(ws + WS_WUQ) + (size_t)(96 * h) * 384;
;       for (int idx = tid; idx < 96 * 48; idx += 512) { const int r = idx / 48, c = idx % 48; *(LAS u32x4*)(wl + r * WQS + c * 8) = *(const u32x4*)(W + r * 384 + c * 8); } }
;     __syncthreads();
;     {
;         bf16_t* Q = (bf16_t*)(ws + WS_Q);
;         f32x4 gvv[6];
; #pragma unroll
;         for (int n = 0; n < 6; ++n) gvv[n] = *(const f32x4*)(p.in[8] + 16 * n + 4 * fq);
; #pragma unroll 1
;         for (int pb = blk_begin + 2 * w; pb < blk_end; pb += 16) {
;             const bool two = (pb + 1) < blk_end;
;             const int blk1 = two ? pb + 1 : pb;
;             const int rowm[2] = {16 * pb + fr, 16 * blk1 + fr};
;             bf16x8 af[2][12]; float ssv[2];
.LBB0_503:
	s_or_b64 exec, exec, s[10:11]
	v_cndmask_b32_e64 v0, 0, v142, s[2:3]
	v_fmac_f32_e32 v0, 0xbf549a78, v5
	v_cndmask_b32_e64 v5, 0, v142, s[4:5]
	v_exp_f32_e32 v0, v0
	v_fmac_f32_e32 v5, 0xbf549a78, v4
	v_exp_f32_e32 v4, v5
	v_cndmask_b32_e64 v5, 0, v143, s[2:3]
	v_ldexp_f32 v154, v0, v5
	v_cndmask_b32_e64 v0, 0, v143, s[4:5]
	v_ldexp_f32 v155, v4, v0
	v_cndmask_b32_e32 v0, 0, v142, vcc
	v_fmac_f32_e32 v0, 0xbf549a78, v3
	v_exp_f32_e32 v0, v0
	v_cndmask_b32_e64 v3, 0, v142, s[0:1]
	v_fmac_f32_e32 v3, 0xbf549a78, v2
	v_exp_f32_e32 v2, v3
	v_cndmask_b32_e32 v3, 0, v143, vcc
	v_ldexp_f32 v156, v0, v3
	v_cndmask_b32_e64 v0, 0, v143, s[0:1]
	s_add_i32 s0, s72, 0xffffff00
	s_lshr_b32 s0, s0, 3
	s_mulk_i32 s0, 0x810
	s_lshr_b32 s13, s0, 5
	s_addk_i32 s0, 0x810
	s_lshr_b32 s12, s0, 5
	v_ashrrev_i32_e32 v136, 6, v135
	s_movk_i32 s0, 0xd00
	v_ldexp_f32 v157, v2, v0
	v_mul_lo_u32 v0, v136, s0
	v_and_b32_e32 v158, 15, v135
	v_add_u32_e32 v134, s87, v0
	v_lshl_add_u32 v159, v136, 1, s13
	v_and_b32_e32 v132, 63, v135
	v_cmp_gt_i32_e32 vcc, s12, v159
	v_lshlrev_b32_e32 v114, 3, v128
	v_and_b32_e32 v137, 48, v135
	v_mad_u32_u24 v160, v158, s88, v134
	v_lshlrev_b32_e32 v139, 2, v115
	s_waitcnt lgkmcnt(0)
	s_barrier
	s_and_saveexec_b64 s[4:5], vcc
	s_cbranch_execz .LBB0_518
	v_and_b32_e32 v242, 0x3c, v163
	v_lshlrev_b32_e32 v242, 4, v242
	v_bfe_u32 v243, v163, 4, 2
	v_lshl_add_u32 v243, v243, 1, v163
	v_and_b32_e32 v243, 3, v243
	v_lshl_add_u32 v242, v243, 4, v242
	v_add_u32_e32 v242, v242, v134
	v_and_b32_e32 v243, 15, v163
	v_lshrrev_b32_e32 v226, 1, v243
	v_and_b32_e32 v226, 6, v226
	v_bfe_u32 v227, v163, 4, 2
	v_add_u32_e32 v226, v226, v227
	v_and_b32_e32 v226, 3, v226
	v_lshlrev_b32_e32 v226, 4, v226
	v_lshl_add_u32 v243, v243, 6, v226
	v_add_u32_e32 v243, v243, v134
	v_readlane_b32 s52, v244, 3
	v_readlane_b32 s53, v244, 4
	s_nop 4
	global_load_dwordx4 v[2:5], v139, s[52:53]
	global_load_dwordx4 v[6:9], v139, s[52:53] offset:64
	global_load_dwordx4 v[10:13], v139, s[52:53] offset:128
	global_load_dwordx4 v[14:17], v139, s[52:53] offset:192
	global_load_dwordx4 v[18:21], v139, s[52:53] offset:256
	global_load_dwordx4 v[22:25], v139, s[52:53] offset:320
	v_lshlrev_b32_e32 v0, 4, v128
	v_cmp_lt_i32_e64 s[0:1], v145, v146
	v_lshl_add_u64 v[116:117], s[40:41], 0, v[0:1]
	s_lshl_b32 s14, s13, 4
	v_cndmask_b32_e64 v0, v144, v145, s[0:1]
	v_cmp_lt_i32_e64 s[0:1], v147, v146
	v_lshlrev_b32_e32 v161, 2, v0
	s_mov_b64 s[8:9], 0
	v_cndmask_b32_e64 v0, v144, v147, s[0:1]
	v_lshlrev_b32_e32 v164, 2, v0
	v_mul_u32_u24_e32 v0, 0x310, v158
	s_movk_i32 s0, 0xab
	v_add3_u32 v165, 0, v137, v0
	v_mul_lo_u16_sdwa v0, v132, s0 dst_sel:DWORD dst_unused:UNUSED_PAD src0_sel:BYTE_0 src1_sel:DWORD
	v_lshrrev_b16_e32 v166, 11, v0
	v_mul_lo_u16_e32 v0, 12, v166
	v_sub_u16_e32 v0, v132, v0
	v_lshlrev_b16_e32 v0, 3, v0
	v_and_b32_e32 v0, 0xf8, v0
	v_mul_u32_u24_e32 v26, 0xd0, v166
	v_lshlrev_b32_e32 v0, 1, v0
	s_movk_i32 s0, 0xff
	v_add3_u32 v167, v134, v26, v0
	v_lshl_add_u64 v[118:119], s[44:45], 0, v[0:1]
	v_bitop3_b16 v0, v132, s0, 64 bitop3:0xc8
	v_mul_lo_u16_e32 v0, 0xab, v0
	v_lshrrev_b16_e32 v168, 11, v0
	v_mul_lo_u16_e32 v0, 12, v168
	v_sub_u16_e32 v0, v132, v0
	v_lshlrev_b16_e32 v0, 3, v0
	v_and_b32_e32 v0, 0xf8, v0
	v_mul_u32_u24_e32 v26, 0xd0, v168
	v_lshlrev_b32_e32 v0, 1, v0
	v_add3_u32 v169, v134, v26, v0
	v_lshl_add_u64 v[120:121], s[44:45], 0, v[0:1]
	v_bitop3_b16 v0, v132, s0, v148 bitop3:0xc8
	v_mul_lo_u16_e32 v0, 0xab, v0
	v_lshrrev_b16_e32 v170, 11, v0
	v_mul_lo_u16_e32 v0, 12, v170
	v_sub_u16_e32 v0, v132, v0
	v_lshlrev_b16_e32 v0, 3, v0
	v_and_b32_e32 v0, 0xf8, v0
	v_mul_u32_u24_e32 v26, 0xd0, v170
	v_lshlrev_b32_e32 v0, 1, v0
	v_add3_u32 v171, v134, v26, v0
	v_lshl_add_u64 v[122:123], s[44:45], 0, v[0:1]
	v_lshlrev_b32_e32 v0, 5, v136
	v_or_b32_e32 v172, v170, v0
	v_or_b32_e32 v173, v168, v0
	v_or_b32_e32 v174, v166, v0
	v_or_b32_e32 v175, v0, v158
	v_mov_b32_e32 v176, v159
	v_readlane_b32 s54, v244, 5
	v_readlane_b32 s55, v244, 6
	v_readlane_b32 s56, v244, 7
	v_readlane_b32 s57, v244, 8
	v_readlane_b32 s58, v244, 9
	v_readlane_b32 s59, v244, 10
	v_readlane_b32 s60, v244, 11
	v_readlane_b32 s61, v244, 12
	v_readlane_b32 s62, v244, 13
	v_readlane_b32 s63, v244, 14
	v_readlane_b32 s64, v244, 15
	v_readlane_b32 s65, v244, 16
	v_readlane_b32 s66, v244, 17
	v_readlane_b32 s67, v244, 18
	s_branch .LBB0_506

; #define LAS __attribute__((address_space(3)))
; #define MFMA16(a, b, c) __builtin_amdgcn_mfma_f32_16x16x32_bf16((a), (b), (c), 0, 0, 0)
; __device__ __forceinline__ void qkv_head_unit(const Params& p, LAS unsigned char* lds, int h, int blk_begin, int blk_end) {
;     ...
;         for (int pb = blk_begin + 2 * w; pb < blk_end; pb += 16) {
;             const bool two = (pb + 1) < blk_end;
;             const int blk1 = two ? pb + 1 : pb;
;             const int rowm[2] = {16 * pb + fr, 16 * blk1 + fr};
;             bf16x8 af[2][12]; float ssv[2];
; #pragma unroll
;             for (int m = 0; m < 2; ++m) { ssv[m] = ss_cq[rowm[m]];
; #pragma unroll
;                 for (int ks = 0; ks < 12; ++ks) af[m][ks] = *(const bf16x8*)(P + (size_t)rowm[m] * INP + 32 * ks + 8 * fq); }
;             f32x4 acc[2][6];
; #pragma unroll
;             for (int m = 0; m < 2; ++m)
; #pragma unroll
;                 for (int n = 0; n < 6; ++n) acc[m][n] = (f32x4){0.f, 0.f, 0.f, 0.f};
; #pragma unroll
;             for (int ks = 0; ks < 12; ++ks)
; #pragma unroll
;                 for (int n = 0; n < 6; ++n) { const bf16x8 bw = *(const LAS bf16x8*)(wl + (16 * n + fr) * WQS + 32 * ks + 8 * fq);
;                     acc[0][n] = MFMA16(bw, af[0][ks], acc[0][n]); acc[1][n] = MFMA16(bw, af[1][ks], acc[1][n]); }
.LBB0_506:
	v_add_u32_e32 v0, 1, v176
	v_cmp_gt_i32_e64 s[2:3], s12, v0
	v_add_u32_e32 v126, s14, v175
	v_ashrrev_i32_e32 v127, 31, v126
	v_cndmask_b32_e64 v0, v176, v0, s[2:3]
	v_lshlrev_b32_e32 v177, 4, v0
	v_or_b32_e32 v124, v177, v158
	v_lshl_add_u64 v[26:27], v[126:127], 2, s[22:23]
	v_ashrrev_i32_e32 v125, 31, v124
	global_load_dword v0, v[26:27], off
	v_lshl_add_u64 v[30:31], v[124:125], 2, s[22:23]
	v_and_b32_e32 v227, 3, v163
	v_bfe_u32 v226, v163, 2, 4
	global_load_dword v125, v[30:31], off
	v_lshlrev_b32_e32 v227, 4, v227
	v_sub_u32_e32 v228, v116, v137
	v_and_b32_e32 v230, -16, v126
	v_add_u32_e32 v228, v228, v227
	v_mov_b32_e32 v229, v117
	v_add_u32_e32 v230, v230, v226
	v_add_u32_e32 v231, v177, v226
	v_mad_i64_i32 v[26:27], s[0:1], v230, s89, v[228:229]
	v_mad_i64_i32 v[30:31], s[0:1], v231, s89, v[228:229]
	global_load_dwordx4 v[178:181], v[26:27], off
	global_load_dwordx4 v[182:185], v[30:31], off
	global_load_dwordx4 v[106:109], v[26:27], off offset:64
	global_load_dwordx4 v[110:113], v[30:31], off offset:64
	global_load_dwordx4 v[98:101], v[26:27], off offset:128
	global_load_dwordx4 v[102:105], v[30:31], off offset:128
	global_load_dwordx4 v[90:93], v[26:27], off offset:192
	global_load_dwordx4 v[94:97], v[30:31], off offset:192
	global_load_dwordx4 v[82:85], v[26:27], off offset:256
	global_load_dwordx4 v[86:89], v[30:31], off offset:256
	global_load_dwordx4 v[74:77], v[26:27], off offset:320
	global_load_dwordx4 v[78:81], v[30:31], off offset:320
	global_load_dwordx4 v[66:69], v[26:27], off offset:384
	global_load_dwordx4 v[70:73], v[30:31], off offset:384
	global_load_dwordx4 v[58:61], v[26:27], off offset:448
	global_load_dwordx4 v[62:65], v[30:31], off offset:448
	global_load_dwordx4 v[50:53], v[26:27], off offset:512
	global_load_dwordx4 v[54:57], v[30:31], off offset:512
	global_load_dwordx4 v[42:45], v[26:27], off offset:576
	global_load_dwordx4 v[46:49], v[30:31], off offset:576
	global_load_dwordx4 v[34:37], v[26:27], off offset:640
	global_load_dwordx4 v[38:41], v[30:31], off offset:640
	s_nop 0
	global_load_dwordx4 v[26:29], v[26:27], off offset:704
	global_load_dwordx4 v[30:33], v[30:31], off offset:704
	s_waitcnt vmcnt(23)
	ds_write_b128 v242, v[178:181]
	ds_read_b128 v[178:181], v243
	s_waitcnt vmcnt(22)
	ds_write_b128 v242, v[182:185] offset:1024
	ds_read_b128 v[182:185], v243 offset:1024
	s_waitcnt vmcnt(21)
	ds_write_b128 v242, v[106:109] offset:2048
	ds_read_b128 v[106:109], v243 offset:2048
	s_waitcnt vmcnt(20)
	ds_write_b128 v242, v[110:113]
	ds_read_b128 v[110:113], v243
	ds_read_b128 v[226:229], v165 offset:0
	ds_read_b128 v[230:233], v165 offset:12544
	ds_read_b128 v[234:237], v165 offset:25088
	ds_read_b128 v[238:241], v165 offset:37632
	s_waitcnt lgkmcnt(3)
	v_mfma_f32_16x16x32_bf16 v[186:189], v[226:229], v[178:181], 0
	v_fmamk_f32 v0, v0, 0x3b2aaaab, v140
	v_rsq_f32_e32 v0, v0
	v_mfma_f32_16x16x32_bf16 v[190:193], v[226:229], v[182:185], 0
	ds_read_b128 v[226:229], v165 offset:50176
	s_waitcnt lgkmcnt(3)
	v_mfma_f32_16x16x32_bf16 v[194:197], v[230:233], v[178:181], 0
	v_mfma_f32_16x16x32_bf16 v[198:201], v[230:233], v[182:185], 0
	ds_read_b128 v[230:233], v165 offset:62720
	s_waitcnt vmcnt(19)
	ds_write_b128 v242, v[98:101] offset:1024
	ds_read_b128 v[98:101], v243 offset:1024
	s_waitcnt vmcnt(18)
	ds_write_b128 v242, v[102:105] offset:2048
	ds_read_b128 v[102:105], v243 offset:2048
	s_waitcnt lgkmcnt(7)
	v_mfma_f32_16x16x32_bf16 v[202:205], v[234:237], v[178:181], 0
	v_mfma_f32_16x16x32_bf16 v[206:209], v[234:237], v[182:185], 0
	ds_read_b128 v[234:237], v165 offset:64
	s_waitcnt lgkmcnt(7)
	v_mfma_f32_16x16x32_bf16 v[210:213], v[238:241], v[178:181], 0
	v_mfma_f32_16x16x32_bf16 v[214:217], v[238:241], v[182:185], 0
	ds_read_b128 v[238:241], v165 offset:12608
	s_waitcnt lgkmcnt(7)
	v_mfma_f32_16x16x32_bf16 v[218:221], v[226:229], v[178:181], 0
	v_mfma_f32_16x16x32_bf16 v[222:225], v[226:229], v[182:185], 0
	ds_read_b128 v[226:229], v165 offset:25152
	s_waitcnt lgkmcnt(7)
	v_mfma_f32_16x16x32_bf16 v[178:181], v[230:233], v[178:181], 0
	v_mfma_f32_16x16x32_bf16 v[182:185], v[230:233], v[182:185], 0
	ds_read_b128 v[230:233], v165 offset:37696
	s_waitcnt lgkmcnt(3)
	v_mfma_f32_16x16x32_bf16 v[186:189], v[234:237], v[106:109], v[186:189]
	v_mfma_f32_16x16x32_bf16 v[190:193], v[234:237], v[110:113], v[190:193]
	ds_read_b128 v[234:237], v165 offset:50240
	s_waitcnt lgkmcnt(3)
	v_mfma_f32_16x16x32_bf16 v[194:197], v[238:241], v[106:109], v[194:197]
	v_mfma_f32_16x16x32_bf16 v[198:201], v[238:241], v[110:113], v[198:201]
	ds_read_b128 v[238:241], v165 offset:62784
	s_waitcnt vmcnt(17)
	ds_write_b128 v242, v[90:93]
	ds_read_b128 v[90:93], v243
	s_waitcnt vmcnt(16)
	ds_write_b128 v242, v[94:97] offset:1024
	ds_read_b128 v[94:97], v243 offset:1024
	s_waitcnt lgkmcnt(7)
	v_mfma_f32_16x16x32_bf16 v[202:205], v[226:229], v[106:109], v[202:205]
	v_mfma_f32_16x16x32_bf16 v[206:209], v[226:229], v[110:113], v[206:209]
	ds_read_b128 v[226:229], v165 offset:128
	s_waitcnt lgkmcnt(7)
	v_mfma_f32_16x16x32_bf16 v[210:213], v[230:233], v[106:109], v[210:213]
	v_mfma_f32_16x16x32_bf16 v[214:217], v[230:233], v[110:113], v[214:217]
	ds_read_b128 v[230:233], v165 offset:12672
	s_waitcnt lgkmcnt(7)
	v_mfma_f32_16x16x32_bf16 v[218:221], v[234:237], v[106:109], v[218:221]
	v_mfma_f32_16x16x32_bf16 v[222:225], v[234:237], v[110:113], v[222:225]
	ds_read_b128 v[234:237], v165 offset:25216
	s_waitcnt lgkmcnt(7)
	v_mfma_f32_16x16x32_bf16 v[178:181], v[238:241], v[106:109], v[178:181]
	v_mfma_f32_16x16x32_bf16 v[182:185], v[238:241], v[110:113], v[182:185]
	ds_read_b128 v[238:241], v165 offset:37760
	s_waitcnt lgkmcnt(3)
; #define LAS __attribute__((address_space(3)))
; #define MFMA16(a, b, c) __builtin_amdgcn_mfma_f32_16x16x32_bf16((a), (b), (c), 0, 0, 0)
; __device__ __forceinline__ void qkv_head_unit(const Params& p, LAS unsigned char* lds, int h, int blk_begin, int blk_end) {
;     ...
;             for (int ks = 0; ks < 12; ++ks)
; #pragma unroll
;                 for (int n = 0; n < 6; ++n) { const bf16x8 bw = *(const LAS bf16x8*)(wl + (16 * n + fr) * WQS + 32 * ks + 8 * fq);
;                     acc[0][n] = MFMA16(bw, af[0][ks], acc[0][n]); acc[1][n] = MFMA16(bw, af[1][ks], acc[1][n]); }
	v_mfma_f32_16x16x32_bf16 v[186:189], v[226:229], v[98:101], v[186:189]
	v_mfma_f32_16x16x32_bf16 v[190:193], v[226:229], v[102:105], v[190:193]
	ds_read_b128 v[226:229], v165 offset:50304
	s_waitcnt lgkmcnt(3)
	v_mfma_f32_16x16x32_bf16 v[194:197], v[230:233], v[98:101], v[194:197]
	v_mfma_f32_16x16x32_bf16 v[198:201], v[230:233], v[102:105], v[198:201]
	ds_read_b128 v[230:233], v165 offset:62848
	s_waitcnt vmcnt(15)
	ds_write_b128 v242, v[82:85] offset:2048
	ds_read_b128 v[82:85], v243 offset:2048
	s_waitcnt vmcnt(14)
	ds_write_b128 v242, v[86:89]
	ds_read_b128 v[86:89], v243
	s_waitcnt lgkmcnt(7)
	v_mfma_f32_16x16x32_bf16 v[202:205], v[234:237], v[98:101], v[202:205]
	v_mfma_f32_16x16x32_bf16 v[206:209], v[234:237], v[102:105], v[206:209]
	ds_read_b128 v[234:237], v165 offset:192
	s_waitcnt lgkmcnt(7)
	v_mfma_f32_16x16x32_bf16 v[210:213], v[238:241], v[98:101], v[210:213]
	v_mfma_f32_16x16x32_bf16 v[214:217], v[238:241], v[102:105], v[214:217]
	ds_read_b128 v[238:241], v165 offset:12736
	s_waitcnt lgkmcnt(7)
	v_mfma_f32_16x16x32_bf16 v[218:221], v[226:229], v[98:101], v[218:221]
	v_mfma_f32_16x16x32_bf16 v[222:225], v[226:229], v[102:105], v[222:225]
	ds_read_b128 v[226:229], v165 offset:25280
	s_waitcnt lgkmcnt(7)
	v_mfma_f32_16x16x32_bf16 v[178:181], v[230:233], v[98:101], v[178:181]
	v_mfma_f32_16x16x32_bf16 v[182:185], v[230:233], v[102:105], v[182:185]
	ds_read_b128 v[230:233], v165 offset:37824
	s_waitcnt lgkmcnt(3)
	v_mfma_f32_16x16x32_bf16 v[186:189], v[234:237], v[90:93], v[186:189]
	v_mfma_f32_16x16x32_bf16 v[190:193], v[234:237], v[94:97], v[190:193]
	ds_read_b128 v[234:237], v165 offset:50368
	s_waitcnt lgkmcnt(3)
	v_mfma_f32_16x16x32_bf16 v[194:197], v[238:241], v[90:93], v[194:197]
	v_mfma_f32_16x16x32_bf16 v[198:201], v[238:241], v[94:97], v[198:201]
	ds_read_b128 v[238:241], v165 offset:62912
	s_waitcnt vmcnt(13)
	ds_write_b128 v242, v[74:77] offset:1024
	ds_read_b128 v[74:77], v243 offset:1024
	s_waitcnt vmcnt(12)
	ds_write_b128 v242, v[78:81] offset:2048
	ds_read_b128 v[78:81], v243 offset:2048
	s_waitcnt lgkmcnt(7)
	v_mfma_f32_16x16x32_bf16 v[202:205], v[226:229], v[90:93], v[202:205]
	v_mfma_f32_16x16x32_bf16 v[206:209], v[226:229], v[94:97], v[206:209]
	ds_read_b128 v[226:229], v165 offset:256
	s_waitcnt lgkmcnt(7)
	v_mfma_f32_16x16x32_bf16 v[210:213], v[230:233], v[90:93], v[210:213]
	v_mfma_f32_16x16x32_bf16 v[214:217], v[230:233], v[94:97], v[214:217]
	ds_read_b128 v[230:233], v165 offset:12800
	s_waitcnt lgkmcnt(7)
	v_mfma_f32_16x16x32_bf16 v[218:221], v[234:237], v[90:93], v[218:221]
	v_mfma_f32_16x16x32_bf16 v[222:225], v[234:237], v[94:97], v[222:225]
	ds_read_b128 v[234:237], v165 offset:25344
	s_waitcnt lgkmcnt(7)
	v_mfma_f32_16x16x32_bf16 v[178:181], v[238:241], v[90:93], v[178:181]
	v_mfma_f32_16x16x32_bf16 v[182:185], v[238:241], v[94:97], v[182:185]
	ds_read_b128 v[238:241], v165 offset:37888
	s_waitcnt lgkmcnt(3)
	v_mfma_f32_16x16x32_bf16 v[186:189], v[226:229], v[82:85], v[186:189]
	v_mfma_f32_16x16x32_bf16 v[190:193], v[226:229], v[86:89], v[190:193]
	ds_read_b128 v[226:229], v165 offset:50432
	s_waitcnt lgkmcnt(3)
	v_mfma_f32_16x16x32_bf16 v[194:197], v[230:233], v[82:85], v[194:197]
	v_mfma_f32_16x16x32_bf16 v[198:201], v[230:233], v[86:89], v[198:201]
	ds_read_b128 v[230:233], v165 offset:62976
	s_waitcnt vmcnt(11)
	ds_write_b128 v242, v[66:69]
	ds_read_b128 v[66:69], v243
	s_waitcnt vmcnt(10)
	ds_write_b128 v242, v[70:73] offset:1024
	ds_read_b128 v[70:73], v243 offset:1024
	s_waitcnt lgkmcnt(7)
	v_mfma_f32_16x16x32_bf16 v[202:205], v[234:237], v[82:85], v[202:205]
	v_mfma_f32_16x16x32_bf16 v[206:209], v[234:237], v[86:89], v[206:209]
	ds_read_b128 v[234:237], v165 offset:320
	s_waitcnt lgkmcnt(7)
	v_mfma_f32_16x16x32_bf16 v[210:213], v[238:241], v[82:85], v[210:213]
	v_mfma_f32_16x16x32_bf16 v[214:217], v[238:241], v[86:89], v[214:217]
	ds_read_b128 v[238:241], v165 offset:12864
	s_waitcnt lgkmcnt(7)
	v_mfma_f32_16x16x32_bf16 v[218:221], v[226:229], v[82:85], v[218:221]
	v_mfma_f32_16x16x32_bf16 v[222:225], v[226:229], v[86:89], v[222:225]
	ds_read_b128 v[226:229], v165 offset:25408
	s_waitcnt lgkmcnt(7)
	v_mfma_f32_16x16x32_bf16 v[178:181], v[230:233], v[82:85], v[178:181]
	v_mfma_f32_16x16x32_bf16 v[182:185], v[230:233], v[86:89], v[182:185]
	ds_read_b128 v[230:233], v165 offset:37952
	s_waitcnt lgkmcnt(3)
	v_mfma_f32_16x16x32_bf16 v[186:189], v[234:237], v[74:77], v[186:189]
	v_mfma_f32_16x16x32_bf16 v[190:193], v[234:237], v[78:81], v[190:193]
	ds_read_b128 v[234:237], v165 offset:50496
	s_waitcnt lgkmcnt(3)
	v_mfma_f32_16x16x32_bf16 v[194:197], v[238:241], v[74:77], v[194:197]
	v_mfma_f32_16x16x32_bf16 v[198:201], v[238:241], v[78:81], v[198:201]
	ds_read_b128 v[238:241], v165 offset:63040
	s_waitcnt vmcnt(9)
	ds_write_b128 v242, v[58:61] offset:2048
	ds_read_b128 v[58:61], v243 offset:2048
	s_waitcnt vmcnt(8)
	ds_write_b128 v242, v[62:65]
	ds_read_b128 v[62:65], v243
	s_waitcnt lgkmcnt(7)
	v_mfma_f32_16x16x32_bf16 v[202:205], v[226:229], v[74:77], v[202:205]
	v_mfma_f32_16x16x32_bf16 v[206:209], v[226:229], v[78:81], v[206:209]
	ds_read_b128 v[226:229], v165 offset:384
	s_waitcnt lgkmcnt(7)
	v_mfma_f32_16x16x32_bf16 v[210:213], v[230:233], v[74:77], v[210:213]
	v_mfma_f32_16x16x32_bf16 v[214:217], v[230:233], v[78:81], v[214:217]
	ds_read_b128 v[230:233], v165 offset:12928
	s_waitcnt lgkmcnt(7)
	v_mfma_f32_16x16x32_bf16 v[218:221], v[234:237], v[74:77], v[218:221]
	v_mfma_f32_16x16x32_bf16 v[222:225], v[234:237], v[78:81], v[222:225]
	ds_read_b128 v[234:237], v165 offset:25472
	s_waitcnt lgkmcnt(7)
; #define LAS __attribute__((address_space(3)))
; #define MFMA16(a, b, c) __builtin_amdgcn_mfma_f32_16x16x32_bf16((a), (b), (c), 0, 0, 0)
; __device__ __forceinline__ void qkv_head_unit(const Params& p, LAS unsigned char* lds, int h, int blk_begin, int blk_end) {
;     ...
;             for (int ks = 0; ks < 12; ++ks)
; #pragma unroll
;                 for (int n = 0; n < 6; ++n) { const bf16x8 bw = *(const LAS bf16x8*)(wl + (16 * n + fr) * WQS + 32 * ks + 8 * fq);
;                     acc[0][n] = MFMA16(bw, af[0][ks], acc[0][n]); acc[1][n] = MFMA16(bw, af[1][ks], acc[1][n]); }
	v_mfma_f32_16x16x32_bf16 v[178:181], v[238:241], v[74:77], v[178:181]
	v_mfma_f32_16x16x32_bf16 v[182:185], v[238:241], v[78:81], v[182:185]
	ds_read_b128 v[238:241], v165 offset:38016
	s_waitcnt lgkmcnt(3)
	v_mfma_f32_16x16x32_bf16 v[186:189], v[226:229], v[66:69], v[186:189]
	v_mfma_f32_16x16x32_bf16 v[190:193], v[226:229], v[70:73], v[190:193]
	ds_read_b128 v[226:229], v165 offset:50560
	s_waitcnt lgkmcnt(3)
	v_mfma_f32_16x16x32_bf16 v[194:197], v[230:233], v[66:69], v[194:197]
	v_mfma_f32_16x16x32_bf16 v[198:201], v[230:233], v[70:73], v[198:201]
	ds_read_b128 v[230:233], v165 offset:63104
	s_waitcnt vmcnt(7)
	ds_write_b128 v242, v[50:53] offset:1024
	ds_read_b128 v[50:53], v243 offset:1024
	s_waitcnt vmcnt(6)
	ds_write_b128 v242, v[54:57] offset:2048
	ds_read_b128 v[54:57], v243 offset:2048
	s_waitcnt lgkmcnt(7)
	v_mfma_f32_16x16x32_bf16 v[202:205], v[234:237], v[66:69], v[202:205]
	v_mfma_f32_16x16x32_bf16 v[206:209], v[234:237], v[70:73], v[206:209]
	ds_read_b128 v[234:237], v165 offset:448
	s_waitcnt lgkmcnt(7)
	v_mfma_f32_16x16x32_bf16 v[210:213], v[238:241], v[66:69], v[210:213]
	v_mfma_f32_16x16x32_bf16 v[214:217], v[238:241], v[70:73], v[214:217]
	ds_read_b128 v[238:241], v165 offset:12992
	s_waitcnt lgkmcnt(7)
	v_mfma_f32_16x16x32_bf16 v[218:221], v[226:229], v[66:69], v[218:221]
	v_mfma_f32_16x16x32_bf16 v[222:225], v[226:229], v[70:73], v[222:225]
	ds_read_b128 v[226:229], v165 offset:25536
	s_waitcnt lgkmcnt(7)
	v_mfma_f32_16x16x32_bf16 v[178:181], v[230:233], v[66:69], v[178:181]
	v_mfma_f32_16x16x32_bf16 v[182:185], v[230:233], v[70:73], v[182:185]
	ds_read_b128 v[230:233], v165 offset:38080
	s_waitcnt lgkmcnt(3)
	v_mfma_f32_16x16x32_bf16 v[186:189], v[234:237], v[58:61], v[186:189]
	v_mfma_f32_16x16x32_bf16 v[190:193], v[234:237], v[62:65], v[190:193]
	ds_read_b128 v[234:237], v165 offset:50624
	s_waitcnt lgkmcnt(3)
	v_mfma_f32_16x16x32_bf16 v[194:197], v[238:241], v[58:61], v[194:197]
	v_mfma_f32_16x16x32_bf16 v[198:201], v[238:241], v[62:65], v[198:201]
	ds_read_b128 v[238:241], v165 offset:63168
	s_waitcnt vmcnt(5)
	ds_write_b128 v242, v[42:45]
	ds_read_b128 v[42:45], v243
	s_waitcnt vmcnt(4)
	ds_write_b128 v242, v[46:49] offset:1024
	ds_read_b128 v[46:49], v243 offset:1024
	s_waitcnt lgkmcnt(7)
	v_mfma_f32_16x16x32_bf16 v[202:205], v[226:229], v[58:61], v[202:205]
	v_mfma_f32_16x16x32_bf16 v[206:209], v[226:229], v[62:65], v[206:209]
	ds_read_b128 v[226:229], v165 offset:512
	s_waitcnt lgkmcnt(7)
	v_mfma_f32_16x16x32_bf16 v[210:213], v[230:233], v[58:61], v[210:213]
	v_mfma_f32_16x16x32_bf16 v[214:217], v[230:233], v[62:65], v[214:217]
	ds_read_b128 v[230:233], v165 offset:13056
	s_waitcnt lgkmcnt(7)
	v_mfma_f32_16x16x32_bf16 v[218:221], v[234:237], v[58:61], v[218:221]
	v_mfma_f32_16x16x32_bf16 v[222:225], v[234:237], v[62:65], v[222:225]
	ds_read_b128 v[234:237], v165 offset:25600
	s_waitcnt lgkmcnt(7)
	v_mfma_f32_16x16x32_bf16 v[178:181], v[238:241], v[58:61], v[178:181]
	v_mfma_f32_16x16x32_bf16 v[182:185], v[238:241], v[62:65], v[182:185]
	ds_read_b128 v[238:241], v165 offset:38144
	s_waitcnt lgkmcnt(3)
	v_mfma_f32_16x16x32_bf16 v[186:189], v[226:229], v[50:53], v[186:189]
	v_mfma_f32_16x16x32_bf16 v[190:193], v[226:229], v[54:57], v[190:193]
	ds_read_b128 v[226:229], v165 offset:50688
	s_waitcnt lgkmcnt(3)
	v_mfma_f32_16x16x32_bf16 v[194:197], v[230:233], v[50:53], v[194:197]
	v_mfma_f32_16x16x32_bf16 v[198:201], v[230:233], v[54:57], v[198:201]
	ds_read_b128 v[230:233], v165 offset:63232
	s_waitcnt vmcnt(3)
	ds_write_b128 v242, v[34:37] offset:2048
	ds_read_b128 v[34:37], v243 offset:2048
	s_waitcnt vmcnt(2)
	ds_write_b128 v242, v[38:41]
	ds_read_b128 v[38:41], v243
	s_waitcnt lgkmcnt(7)
	v_mfma_f32_16x16x32_bf16 v[202:205], v[234:237], v[50:53], v[202:205]
	v_mfma_f32_16x16x32_bf16 v[206:209], v[234:237], v[54:57], v[206:209]
	ds_read_b128 v[234:237], v165 offset:576
	s_waitcnt lgkmcnt(7)
	v_mfma_f32_16x16x32_bf16 v[210:213], v[238:241], v[50:53], v[210:213]
	v_mfma_f32_16x16x32_bf16 v[214:217], v[238:241], v[54:57], v[214:217]
	ds_read_b128 v[238:241], v165 offset:13120
	s_waitcnt lgkmcnt(7)
	v_mfma_f32_16x16x32_bf16 v[218:221], v[226:229], v[50:53], v[218:221]
	v_mfma_f32_16x16x32_bf16 v[222:225], v[226:229], v[54:57], v[222:225]
	ds_read_b128 v[226:229], v165 offset:25664
	s_waitcnt lgkmcnt(7)
	v_mfma_f32_16x16x32_bf16 v[178:181], v[230:233], v[50:53], v[178:181]
	v_mfma_f32_16x16x32_bf16 v[182:185], v[230:233], v[54:57], v[182:185]
	ds_read_b128 v[230:233], v165 offset:38208
	s_waitcnt lgkmcnt(3)
	v_mfma_f32_16x16x32_bf16 v[186:189], v[234:237], v[42:45], v[186:189]
	v_mfma_f32_16x16x32_bf16 v[190:193], v[234:237], v[46:49], v[190:193]
	ds_read_b128 v[234:237], v165 offset:50752
	s_waitcnt lgkmcnt(3)
	v_mfma_f32_16x16x32_bf16 v[194:197], v[238:241], v[42:45], v[194:197]
	v_mfma_f32_16x16x32_bf16 v[198:201], v[238:241], v[46:49], v[198:201]
	ds_read_b128 v[238:241], v165 offset:63296
	s_waitcnt vmcnt(1)
	ds_write_b128 v242, v[26:29] offset:1024
	ds_read_b128 v[26:29], v243 offset:1024
	s_waitcnt vmcnt(0)
	ds_write_b128 v242, v[30:33] offset:2048
	ds_read_b128 v[30:33], v243 offset:2048
	s_waitcnt lgkmcnt(7)
	v_mfma_f32_16x16x32_bf16 v[202:205], v[226:229], v[42:45], v[202:205]
	v_mfma_f32_16x16x32_bf16 v[206:209], v[226:229], v[46:49], v[206:209]
	ds_read_b128 v[226:229], v165 offset:640
	s_waitcnt lgkmcnt(7)
	v_mfma_f32_16x16x32_bf16 v[210:213], v[230:233], v[42:45], v[210:213]
	v_mfma_f32_16x16x32_bf16 v[214:217], v[230:233], v[46:49], v[214:217]
	ds_read_b128 v[230:233], v165 offset:13184
	s_waitcnt lgkmcnt(7)
; #define LAS __attribute__((address_space(3)))
; __device__ __forceinline__ float frsq(float x) { return __builtin_amdgcn_rsqf(x); }
; #define MFMA16(a, b, c) __builtin_amdgcn_mfma_f32_16x16x32_bf16((a), (b), (c), 0, 0, 0)
; __device__ __forceinline__ void qkv_head_unit(const Params& p, LAS unsigned char* lds, int h, int blk_begin, int blk_end) {
;     ...
;             for (int ks = 0; ks < 12; ++ks)
; #pragma unroll
;                 for (int n = 0; n < 6; ++n) { const bf16x8 bw = *(const LAS bf16x8*)(wl + (16 * n + fr) * WQS + 32 * ks + 8 * fq);
;                     acc[0][n] = MFMA16(bw, af[0][ks], acc[0][n]); acc[1][n] = MFMA16(bw, af[1][ks], acc[1][n]); }
; #pragma unroll
;             for (int mi = 0; mi < 2; ++mi) {
;                 const bool valid = (mi == 0) || two;
;                 const int t = rowm[mi] % TT;
;                 const float sc = frsq(ssv[mi] * (1.0f / 384.0f) + EPS);
;                 float ssq = 0.f;
; #pragma unroll
;                 for (int n = 0; n < 6; ++n) { acc[mi][n] *= sc; ssq += (acc[mi][n][0] * acc[mi][n][0] + acc[mi][n][1] * acc[mi][n][1]) + (acc[mi][n][2] * acc[mi][n][2] + acc[mi][n][3] * acc[mi][n][3]); }
;                 ssq += __shfl_xor(ssq, 16); ssq += __shfl_xor(ssq, 32);
	v_mfma_f32_16x16x32_bf16 v[218:221], v[234:237], v[42:45], v[218:221]
	v_mfma_f32_16x16x32_bf16 v[222:225], v[234:237], v[46:49], v[222:225]
	ds_read_b128 v[234:237], v165 offset:25728
	s_waitcnt lgkmcnt(7)
	v_mfma_f32_16x16x32_bf16 v[178:181], v[238:241], v[42:45], v[178:181]
	v_mfma_f32_16x16x32_bf16 v[182:185], v[238:241], v[46:49], v[182:185]
	ds_read_b128 v[238:241], v165 offset:38272
	s_waitcnt lgkmcnt(3)
	v_mfma_f32_16x16x32_bf16 v[186:189], v[226:229], v[34:37], v[186:189]
	v_mfma_f32_16x16x32_bf16 v[190:193], v[226:229], v[38:41], v[190:193]
	ds_read_b128 v[226:229], v165 offset:50816
	s_waitcnt lgkmcnt(3)
	v_mfma_f32_16x16x32_bf16 v[194:197], v[230:233], v[34:37], v[194:197]
	v_mfma_f32_16x16x32_bf16 v[198:201], v[230:233], v[38:41], v[198:201]
	ds_read_b128 v[230:233], v165 offset:63360
	s_waitcnt lgkmcnt(3)
	v_mfma_f32_16x16x32_bf16 v[202:205], v[234:237], v[34:37], v[202:205]
	v_mfma_f32_16x16x32_bf16 v[206:209], v[234:237], v[38:41], v[206:209]
	ds_read_b128 v[234:237], v165 offset:704
	s_waitcnt lgkmcnt(3)
	v_mfma_f32_16x16x32_bf16 v[210:213], v[238:241], v[34:37], v[210:213]
	v_mfma_f32_16x16x32_bf16 v[214:217], v[238:241], v[38:41], v[214:217]
	ds_read_b128 v[238:241], v165 offset:13248
	s_waitcnt lgkmcnt(3)
	v_mfma_f32_16x16x32_bf16 v[218:221], v[226:229], v[34:37], v[218:221]
	v_mfma_f32_16x16x32_bf16 v[222:225], v[226:229], v[38:41], v[222:225]
	ds_read_b128 v[226:229], v165 offset:25792
	s_waitcnt lgkmcnt(3)
	v_mfma_f32_16x16x32_bf16 v[178:181], v[230:233], v[34:37], v[178:181]
	v_mfma_f32_16x16x32_bf16 v[182:185], v[230:233], v[38:41], v[182:185]
	ds_read_b128 v[230:233], v165 offset:38336
	s_waitcnt lgkmcnt(3)
	v_mfma_f32_16x16x32_bf16 v[54:57], v[234:237], v[26:29], v[186:189]
	v_mfma_f32_16x16x32_bf16 v[34:37], v[234:237], v[30:33], v[190:193]
	ds_read_b128 v[234:237], v165 offset:50880
	s_waitcnt lgkmcnt(3)
	v_mfma_f32_16x16x32_bf16 v[62:65], v[238:241], v[26:29], v[194:197]
	v_mfma_f32_16x16x32_bf16 v[46:49], v[238:241], v[30:33], v[198:201]
	ds_read_b128 v[238:241], v165 offset:63424
	s_waitcnt lgkmcnt(3)
	v_mfma_f32_16x16x32_bf16 v[58:61], v[226:229], v[26:29], v[202:205]
	v_mfma_f32_16x16x32_bf16 v[50:53], v[226:229], v[30:33], v[206:209]
	s_waitcnt lgkmcnt(2)
	v_mfma_f32_16x16x32_bf16 v[66:69], v[230:233], v[26:29], v[210:213]
	v_mfma_f32_16x16x32_bf16 v[42:45], v[230:233], v[30:33], v[214:217]
	s_waitcnt lgkmcnt(1)
	v_mfma_f32_16x16x32_bf16 v[70:73], v[234:237], v[26:29], v[218:221]
	v_mfma_f32_16x16x32_bf16 v[38:41], v[234:237], v[30:33], v[222:225]
	s_waitcnt lgkmcnt(0)
	v_mfma_f32_16x16x32_bf16 v[78:81], v[238:241], v[26:29], v[178:181]
	v_mfma_f32_16x16x32_bf16 v[26:29], v[238:241], v[30:33], v[182:185]
	s_nop 7
	v_pk_mul_f32 v[68:69], v[0:1], v[68:69] op_sel_hi:[0,1]
	v_pk_mul_f32 v[66:67], v[0:1], v[66:67] op_sel_hi:[0,1]
	v_mul_f32_e64 v72, v0, v72
	v_mul_f32_e64 v73, v0, v73
	v_pk_mul_f32 v[70:71], v[0:1], v[70:71] op_sel_hi:[0,1]
	v_mul_f32_e64 v32, v0, v54
	v_mul_f32_e64 v33, v0, v55
	v_pk_mul_f32 v[76:77], v[0:1], v[58:59] op_sel_hi:[0,1]
	v_mul_f32_e32 v58, v33, v33
	v_pk_mul_f32 v[30:31], v[0:1], v[56:57] op_sel_hi:[0,1]
	v_pk_mul_f32 v[74:75], v[0:1], v[60:61] op_sel_hi:[0,1]
	v_mul_f32_e32 v60, v76, v76
	v_pk_fma_f32 v[58:59], v[32:33], v[32:33], v[58:59] op_sel_hi:[1,1,0]
	v_pk_mul_f32 v[56:57], v[0:1], v[62:63] op_sel_hi:[0,1]
	v_mov_b32_e32 v59, v60
	v_mul_f32_e32 v60, v31, v31
	v_mul_f32_e32 v62, v77, v77
	v_pk_fma_f32 v[60:61], v[30:31], v[30:31], v[60:61] op_sel_hi:[1,1,0]
	v_pk_mul_f32 v[54:55], v[0:1], v[64:65] op_sel_hi:[0,1]
	v_mov_b32_e32 v61, v62
	v_pk_add_f32 v[58:59], v[58:59], v[60:61]
	v_mul_f32_e32 v60, v57, v57
	v_mul_f32_e32 v63, v74, v74
	v_pk_fma_f32 v[60:61], v[56:57], v[56:57], v[60:61] op_sel_hi:[1,1,0]
	v_mul_f32_e32 v62, v55, v55
	v_mul_f32_e32 v64, v75, v75
	v_mov_b32_e32 v61, v63
	v_pk_fma_f32 v[62:63], v[54:55], v[54:55], v[62:63] op_sel_hi:[1,1,0]
	v_pk_mul_f32 v[78:79], v[0:1], v[78:79] op_sel_hi:[0,1]
	v_mov_b32_e32 v63, v64
	v_pk_add_f32 v[60:61], v[60:61], v[62:63]
	v_pk_mul_f32 v[62:63], v[68:69], v[68:69]
	v_pk_add_f32 v[58:59], v[58:59], v[60:61]
	v_pk_mul_f32 v[60:61], v[66:67], v[66:67]
	v_pk_mul_f32 v[80:81], v[0:1], v[80:81] op_sel_hi:[0,1]
	v_pk_mov_b32 v[64:65], v[60:61], v[62:63] op_sel:[1,0]
	v_mov_b32_e32 v61, v63
	v_pk_add_f32 v[60:61], v[64:65], v[60:61]
	v_mul_f32_e32 v0, v78, v78
	v_mul_f32_e32 v62, v79, v79
	v_pk_add_f32 v[58:59], v[58:59], v[58:59] op_sel:[0,1] op_sel_hi:[1,0]
	v_pk_add_f32 v[60:61], v[60:61], v[60:61] op_sel:[0,1] op_sel_hi:[1,0]
	v_mov_b32_e32 v59, v0
	v_mov_b32_e32 v61, v62
	v_mul_f32_e32 v0, v71, v71
	v_mul_f32_e32 v63, v80, v80
	v_pk_add_f32 v[58:59], v[58:59], v[60:61]
	v_pk_fma_f32 v[60:61], v[70:71], v[70:71], v[0:1] op_sel_hi:[1,1,0]
	v_mul_f32_e32 v0, v73, v73
	v_mul_f32_e32 v64, v81, v81
	v_mov_b32_e32 v61, v63
	v_pk_fma_f32 v[62:63], v[72:73], v[72:73], v[0:1] op_sel_hi:[1,1,0]
	s_nop 0
	v_mov_b32_e32 v63, v64
	v_pk_add_f32 v[60:61], v[60:61], v[62:63]
	s_nop 0
	v_pk_add_f32 v[58:59], v[58:59], v[60:61]
	s_nop 0
	v_add_f32_e32 v0, v58, v59
	ds_bpermute_b32 v58, v161, v0
	s_waitcnt lgkmcnt(0)
	v_add_f32_e32 v0, v0, v58
	ds_bpermute_b32 v58, v164, v0
	s_waitcnt lgkmcnt(0)
; #define LAS __attribute__((address_space(3)))
; __device__ __forceinline__ unsigned cvt_pk(float lo, float hi) { unsigned r; asm("v_cvt_pk_bf16_f32 %0, %1, %2" : "=v"(r) : "v"(lo), "v"(hi)); return r; }
; __device__ __forceinline__ float frsq(float x) { return __builtin_amdgcn_rsqf(x); }
; __device__ __forceinline__ void qkv_head_unit(const Params& p, LAS unsigned char* lds, int h, int blk_begin, int blk_end) {
;     ...
;                 ssq += __shfl_xor(ssq, 16); ssq += __shfl_xor(ssq, 32);
;                 const float rq = frsq(ssq * (1.0f / 96.0f) + EPS);
; #pragma unroll
;                 for (int n = 0; n < 6; ++n) acc[mi][n] = acc[mi][n] * rq * gvv[n];
; #pragma unroll
;                 for (int i = 0; i < 4; ++i) { float sn, cs; sincos_rr((float)t * frq[i], sn, cs);
;                     const float x1 = acc[mi][4][i], x2 = acc[mi][5][i]; acc[mi][4][i] = x1 * cs - x2 * sn; acc[mi][5][i] = x1 * sn + x2 * cs; }
; #pragma unroll
;                 for (int n = 0; n < 6; ++n) { u32x2 wv; wv.x = cvt_pk(acc[mi][n][0] * QSCALE, acc[mi][n][1] * QSCALE); wv.y = cvt_pk(acc[mi][n][2] * QSCALE, acc[mi][n][3] * QSCALE); *(LAS u32x2*)(stg + fr * 104 + 16 * n + 4 * fq) = wv; }
;                 asm volatile("s_waitcnt lgkmcnt(0)" ::: "memory");
; #pragma unroll
;                 for (int j = 0; j < 3; ++j) { const int c = lane + 64 * j, rw = c / 12, cc = c % 12; const int row2 = 16 * (mi ? blk1 : pb) + rw, b2 = row2 / TT, t2 = row2 % TT;
;                     const u32x4 v = *(const LAS u32x4*)(stg + rw * 104 + 8 * cc);
;                     if (valid && t2 >= NMETA) *(u32x4*)(Q + (((size_t)(b2 * NH + h)) * SEQ + (t2 - NMETA)) * QKH + 8 * cc) = v; }
	v_add_f32_e32 v0, v0, v58
	v_fmamk_f32 v0, v0, 0x3c2aaaab, v140
	v_rsq_f32_e32 v0, v0
	s_nop 0
	v_pk_mul_f32 v[32:33], v[32:33], v[0:1] op_sel_hi:[1,0]
	v_pk_mul_f32 v[30:31], v[30:31], v[0:1] op_sel_hi:[1,0]
	v_pk_mul_f32 v[64:65], v[2:3], v[32:33]
	v_pk_mul_f32 v[32:33], v[54:55], v[0:1] op_sel_hi:[1,0]
	v_pk_mul_f32 v[62:63], v[4:5], v[30:31]
	v_pk_mul_f32 v[30:31], v[56:57], v[0:1] op_sel_hi:[1,0]
	v_pk_mul_f32 v[58:59], v[8:9], v[32:33]
	v_pk_mul_f32 v[32:33], v[74:75], v[0:1] op_sel_hi:[1,0]
	v_pk_mul_f32 v[60:61], v[6:7], v[30:31]
	v_pk_mul_f32 v[30:31], v[76:77], v[0:1] op_sel_hi:[1,0]
	v_pk_mul_f32 v[54:55], v[12:13], v[32:33]
	v_pk_mul_f32 v[32:33], v[66:67], v[0:1] op_sel_hi:[1,0]
	v_pk_mul_f32 v[66:67], v[70:71], v[0:1] op_sel_hi:[1,0]
	v_pk_mul_f32 v[56:57], v[10:11], v[30:31]
	v_pk_mul_f32 v[30:31], v[68:69], v[0:1] op_sel_hi:[1,0]
	v_pk_mul_f32 v[68:69], v[72:73], v[0:1] op_sel_hi:[1,0]
	v_pk_mul_f32 v[72:73], v[18:19], v[66:67]
	v_pk_mul_f32 v[70:71], v[78:79], v[0:1] op_sel_hi:[1,0]
	v_pk_mul_f32 v[66:67], v[80:81], v[0:1] op_sel_hi:[1,0]
	v_mul_hi_i32 v0, v126, s90
	v_lshrrev_b32_e32 v74, 31, v0
	v_ashrrev_i32_e32 v0, 7, v0
	v_add_u32_e32 v0, v0, v74
	v_mul_lo_u32 v0, v0, s86
	v_sub_u32_e32 v0, v126, v0
	v_cvt_f32_i32_e32 v0, v0
	v_pk_mul_f32 v[70:71], v[22:23], v[70:71]
	v_mov_b32_e32 v76, v72
	v_mov_b32_e32 v77, v70
	v_mul_f32_e32 v74, v154, v0
	v_mul_f32_e32 v75, 0.15915494, v74
	v_rndne_f32_e32 v75, v75
	v_fmac_f32_e32 v74, 0xc0c90fdb, v75
	v_fmac_f32_e32 v74, 0x343bbd2e, v75
	v_mul_f32_e32 v74, 0.15915494, v74
	v_sin_f32_e32 v75, v74
	v_cos_f32_e32 v74, v74
	v_mul_f32_e32 v70, v155, v0
	v_mul_f32_e32 v72, 0.15915494, v70
	v_rndne_f32_e32 v72, v72
	v_pk_mul_f32 v[78:79], v[74:75], v[76:77]
	v_fmac_f32_e32 v70, 0xc0c90fdb, v72
	v_sub_f32_e32 v80, v78, v79
	v_mov_b32_e32 v78, v75
	v_mov_b32_e32 v79, v74
	v_fmac_f32_e32 v70, 0x343bbd2e, v72
	v_pk_mul_f32 v[74:75], v[78:79], v[76:77]
	v_mul_f32_e32 v70, 0.15915494, v70
	v_add_f32_e32 v76, v74, v75
	v_sin_f32_e32 v75, v70
	v_cos_f32_e32 v74, v70
	v_mov_b32_e32 v70, v73
	v_pk_mul_f32 v[66:67], v[24:25], v[66:67]
	v_pk_mul_f32 v[68:69], v[20:21], v[68:69]
	v_pk_mul_f32 v[72:73], v[74:75], v[70:71]
	v_pk_mul_f32 v[30:31], v[16:17], v[30:31]
	v_sub_f32_e32 v77, v72, v73
	v_mov_b32_e32 v72, v75
	v_mov_b32_e32 v73, v74
	v_pk_mul_f32 v[70:71], v[72:73], v[70:71]
	v_mov_b32_e32 v73, v66
	v_add_f32_e32 v78, v70, v71
	v_mul_f32_e32 v70, v156, v0
	v_mul_f32_e32 v71, 0.15915494, v70
	v_rndne_f32_e32 v71, v71
	v_fmac_f32_e32 v70, 0xc0c90fdb, v71
	v_fmac_f32_e32 v70, 0x343bbd2e, v71
	v_mul_f32_e32 v70, 0.15915494, v70
	v_sin_f32_e32 v71, v70
	v_cos_f32_e32 v70, v70
	v_mul_f32_e32 v0, v157, v0
	v_mul_f32_e32 v66, 0.15915494, v0
	v_mov_b32_e32 v72, v68
	v_rndne_f32_e32 v66, v66
	v_pk_mul_f32 v[74:75], v[70:71], v[72:73]
	v_fmac_f32_e32 v0, 0xc0c90fdb, v66
	v_sub_f32_e32 v79, v74, v75
	v_mov_b32_e32 v74, v71
	v_mov_b32_e32 v75, v70
	v_fmac_f32_e32 v0, 0x343bbd2e, v66
	v_pk_mul_f32 v[70:71], v[74:75], v[72:73]
	v_mul_f32_e32 v0, 0.15915494, v0
	v_add_f32_e32 v72, v70, v71
	v_sin_f32_e32 v71, v0
	v_cos_f32_e32 v70, v0
	v_pk_mul_f32 v[32:33], v[14:15], v[32:33]
	v_mov_b32_e32 v66, v69
	v_mul_f32_e32 v32, 0x3e16c740, v32
	v_pk_mul_f32 v[68:69], v[70:71], v[66:67]
	v_mul_f32_e32 v33, 0x3e16c740, v33
	v_mul_f32_e32 v30, 0x3e16c740, v30
	v_mul_f32_e32 v31, 0x3e16c740, v31
	v_sub_f32_e32 v0, v68, v69
	v_mov_b32_e32 v68, v71
	v_mov_b32_e32 v69, v70
	v_mul_f32_e32 v64, 0x3e16c740, v64
	v_mul_f32_e32 v65, 0x3e16c740, v65
	v_mul_f32_e32 v62, 0x3e16c740, v62
	v_cvt_pk_bf16_f32 v32, v32, v33
	v_cvt_pk_bf16_f32 v33, v30, v31
	v_mul_f32_e32 v30, 0x3e16c740, v80
	v_mul_f32_e32 v31, 0x3e16c740, v77
	v_pk_mul_f32 v[66:67], v[68:69], v[66:67]
	v_cvt_pk_bf16_f32 v64, v64, v65
	v_mul_f32_e32 v63, 0x3e16c740, v63
	v_cvt_pk_bf16_f32 v65, v62, v63
	v_add_u32_e32 v62, v160, v114
	v_mul_f32_e32 v56, 0x3e16c740, v56
	v_mul_f32_e32 v57, 0x3e16c740, v57
	v_cvt_pk_bf16_f32 v30, v30, v31
	v_mul_f32_e32 v31, 0x3e16c740, v79
	v_mul_f32_e32 v0, 0x3e16c740, v0
	v_add_f32_e32 v66, v66, v67
	v_cvt_pk_bf16_f32 v56, v56, v57
	v_mul_f32_e32 v54, 0x3e16c740, v54
	v_mul_f32_e32 v55, 0x3e16c740, v55
	v_cvt_pk_bf16_f32 v57, v54, v55
	ds_write2_b64 v62, v[56:57], v[32:33] offset0:8 offset1:12
	v_cvt_pk_bf16_f32 v31, v31, v0
	v_mul_f32_e32 v0, 0x3e16c740, v76
	v_mul_f32_e32 v32, 0x3e16c740, v78
	v_cvt_pk_bf16_f32 v32, v0, v32
	v_mul_f32_e32 v0, 0x3e16c740, v72
	v_mul_f32_e32 v33, 0x3e16c740, v66
	v_cvt_pk_bf16_f32 v33, v0, v33
	v_add_u32_e32 v0, s14, v174
	ds_write2_b64 v62, v[30:31], v[32:33] offset0:16 offset1:20
	v_mul_hi_i32 v30, v0, s90
	v_mul_f32_e32 v60, 0x3e16c740, v60
	v_mul_f32_e32 v61, 0x3e16c740, v61
	v_lshrrev_b32_e32 v31, 31, v30
	v_ashrrev_i32_e32 v30, 7, v30
	v_cvt_pk_bf16_f32 v60, v60, v61
	v_mul_f32_e32 v58, 0x3e16c740, v58
	v_mul_f32_e32 v59, 0x3e16c740, v59
	v_cvt_pk_bf16_f32 v61, v58, v59
	ds_write2_b64 v62, v[64:65], v[60:61] offset1:4
	v_add_u32_e32 v30, v30, v31
	s_waitcnt lgkmcnt(0)
	v_mul_i32_i24_e32 v31, 0x810, v30
	v_sub_u32_e32 v0, v0, v31
	v_cmp_lt_i32_e64 s[0:1], 15, v0
	s_and_saveexec_b64 s[10:11], s[0:1]
	s_cbranch_execz .LBB0_508
	v_lshl_or_b32 v30, v30, 3, s16
	ds_read_b128 v[54:57], v167
	v_ashrrev_i32_e32 v31, 31, v30
	v_lshlrev_b64 v[30:31], 11, v[30:31]
	v_add_u32_e32 v0, -16, v0
	v_lshl_add_u64 v[30:31], v[30:31], 0, v[0:1]
	v_mad_u64_u32 v[32:33], s[0:1], v30, s91, v[118:119]
	v_mad_i32_i24 v33, v31, s91, v33
	s_waitcnt lgkmcnt(0)
	global_store_dwordx4 v[32:33], v[54:57], off

; __device__ __forceinline__ void qkv_head_unit(const Params& p, LAS unsigned char* lds, int h, int blk_begin, int blk_end) {
;     ...
;     __syncthreads();
;     {
;         bf16_t* Kb = (bf16_t*)(ws + WS_K); bf16_t* Vt = (bf16_t*)(ws + WS_VT);
;         f32x4 gvv[6];
; #pragma unroll
;         for (int n = 0; n < 6; ++n) gvv[n] = *(const f32x4*)(p.in[9] + 16 * n + 4 * fq);
; #pragma unroll 1
;         for (int pb = blk_begin + 2 * w; pb < blk_end; pb += 16) {
;             const bool two = (pb + 1) < blk_end;
;             const int blk1 = two ? pb + 1 : pb;
;             const int rowm[2] = {16 * pb + fr, 16 * blk1 + fr};
;             bf16x8 af[2][8]; float ssv[2]; u32x2 k1v[2], k2v[2];
; #pragma unroll
;             for (int m = 0; m < 2; ++m) { ssv[m] = ss_ckv[rowm[m]]; k1v[m] = *(const u32x2*)(P + (size_t)rowm[m] * INP + C_KR + 4 * fq); k2v[m] = *(const u32x2*)(P + (size_t)rowm[m] * INP + C_KR + 16 + 4 * fq);
; #pragma unroll
;                 for (int ks = 0; ks < 8; ++ks) af[m][ks] = *(const bf16x8*)(P + (size_t)rowm[m] * INP + C_CKV + 32 * ks + 8 * fq); }
.LBB0_521:
	s_or_b64 exec, exec, s[2:3]
	s_waitcnt lgkmcnt(0)
	s_barrier
	s_and_saveexec_b64 s[0:1], vcc
	s_cbranch_execz .LBB0_528
	v_and_b32_e32 v242, 0x3c, v163
	v_lshlrev_b32_e32 v242, 4, v242
	v_bfe_u32 v243, v163, 4, 2
	v_lshl_add_u32 v243, v243, 1, v163
	v_and_b32_e32 v243, 3, v243
	v_lshl_add_u32 v242, v243, 4, v242
	v_add_u32_e32 v242, v242, v134
	v_and_b32_e32 v243, 15, v163
	v_lshrrev_b32_e32 v226, 1, v243
	v_and_b32_e32 v226, 6, v226
	v_bfe_u32 v227, v163, 4, 2
	v_add_u32_e32 v226, v226, v227
	v_and_b32_e32 v226, 3, v226
	v_lshlrev_b32_e32 v226, 4, v226
	v_lshl_add_u32 v243, v243, 6, v226
	v_add_u32_e32 v243, v243, v134
	v_readlane_b32 s52, v244, 3
	v_readlane_b32 s54, v244, 5
	v_readlane_b32 s55, v244, 6
	s_nop 4
	global_load_dwordx4 v[22:25], v139, s[54:55] offset:256
	global_load_dwordx4 v[2:5], v139, s[54:55] offset:320
	global_load_dwordx4 v[6:9], v139, s[54:55]
	global_load_dwordx4 v[10:13], v139, s[54:55] offset:64
	global_load_dwordx4 v[14:17], v139, s[54:55] offset:128
	global_load_dwordx4 v[18:21], v139, s[54:55] offset:192
	v_cmp_lt_i32_e32 vcc, v145, v146
	v_mul_hi_u32 v29, v132, s93
	v_or_b32_e32 v30, 64, v132
	v_cndmask_b32_e32 v26, v144, v145, vcc
	v_cmp_lt_i32_e32 vcc, v147, v146
	v_add_u32_e32 v0, 0, v137
	s_movk_i32 s4, 0xff32
	v_cndmask_b32_e32 v27, v144, v147, vcc
	v_mul_u32_u24_e32 v28, 0x210, v158
	v_or_b32_e32 v31, 0x80, v132
	v_lshlrev_b32_e32 v105, 2, v27
	v_lshrrev_b32_e32 v107, 3, v29
	v_mul_hi_u32 v27, v30, s93
	v_lshlrev_b32_e32 v32, 7, v128
	v_mad_i32_i24 v37, v158, s4, v160
	v_mul_hi_u32 v29, v31, s93
	v_add_u32_e32 v164, v0, v28
	v_mul_u32_u24_e32 v0, 12, v107
	v_lshrrev_b32_e32 v170, 3, v27
	v_lshlrev_b32_e32 v34, 5, v130
	v_add_u32_e32 v166, v37, v32
	v_lshrrev_b32_e32 v171, 3, v29
	v_sub_u32_e32 v0, v132, v0
	v_mul_lo_u32 v32, v170, 12
	v_lshrrev_b32_e32 v36, 1, v132
	v_add_u32_e32 v168, v37, v34
	v_mul_u32_u24_e32 v28, 0xd0, v107
	v_mul_lo_u32 v34, v171, 12
	v_lshlrev_b32_e32 v0, 4, v0
	v_sub_u32_e32 v30, v30, v32
	v_and_b32_e32 v102, 8, v133
	s_movk_i32 s5, 0x210
	v_lshlrev_b32_e32 v33, 5, v129
	v_lshlrev_b32_e32 v39, 5, v36
	v_lshlrev_b32_e32 v104, 6, v36
	v_or_b32_e32 v36, 32, v36
	v_mul_lo_u32 v29, v170, s88
	v_sub_u32_e32 v31, v31, v34
	v_add3_u32 v173, v134, v28, v0
	v_lshl_add_u64 v[108:109], s[48:49], 0, v[0:1]
	v_lshlrev_b32_e32 v0, 4, v30
	v_lshlrev_b32_e32 v35, 5, v131
	s_lshl_b32 s8, s13, 4
	v_mad_u32_u24 v38, v158, s5, 0
	v_lshlrev_b32_e32 v103, 2, v26
	v_lshl_add_u32 v26, v102, 1, v134
	v_add_u32_e32 v167, v37, v33
	v_lshlrev_b32_e32 v27, 5, v36
	v_mul_lo_u32 v33, v171, s88
	v_add3_u32 v174, v134, v29, v0
	v_lshl_add_u64 v[110:111], s[48:49], 0, v[0:1]
	v_lshlrev_b32_e32 v0, 4, v31
	s_mov_b64 s[2:3], 0
	v_lshl_add_u32 v161, v136, 5, s8
	v_add_u32_e32 v165, v38, v137
	v_add_u32_e32 v169, v37, v35
	v_lshlrev_b32_e32 v106, 6, v36
	v_add_u32_e32 v172, v26, v39
	v_add3_u32 v175, v134, v33, v0
	v_lshl_add_u64 v[112:113], s[48:49], 0, v[0:1]
	v_add_u32_e32 v176, v26, v27
	v_readlane_b32 s53, v244, 4
	v_readlane_b32 s56, v244, 7
	v_readlane_b32 s57, v244, 8
	v_readlane_b32 s58, v244, 9
	v_readlane_b32 s59, v244, 10
	v_readlane_b32 s60, v244, 11
	v_readlane_b32 s61, v244, 12
	v_readlane_b32 s62, v244, 13
	v_readlane_b32 s63, v244, 14
	v_readlane_b32 s64, v244, 15
	v_readlane_b32 s65, v244, 16
	v_readlane_b32 s66, v244, 17
	v_readlane_b32 s67, v244, 18
	s_waitcnt vmcnt(5)
	v_mov_b32_e32 v116, v24
	s_waitcnt vmcnt(4)
	v_mov_b32_e32 v117, v4
	v_mov_b32_e32 v4, v25
	v_mov_b32_e32 v118, v22
	v_mov_b32_e32 v119, v2
	v_mov_b32_e32 v2, v23
	s_branch .LBB0_524

; #define LAS __attribute__((address_space(3)))
; #define MFMA16(a, b, c) __builtin_amdgcn_mfma_f32_16x16x32_bf16((a), (b), (c), 0, 0, 0)
; __device__ __forceinline__ void qkv_head_unit(const Params& p, LAS unsigned char* lds, int h, int blk_begin, int blk_end) {
;     ...
;             bf16x8 af[2][8]; float ssv[2]; u32x2 k1v[2], k2v[2];
; #pragma unroll
;             for (int m = 0; m < 2; ++m) { ssv[m] = ss_ckv[rowm[m]]; k1v[m] = *(const u32x2*)(P + (size_t)rowm[m] * INP + C_KR + 4 * fq); k2v[m] = *(const u32x2*)(P + (size_t)rowm[m] * INP + C_KR + 16 + 4 * fq);
; #pragma unroll
;                 for (int ks = 0; ks < 8; ++ks) af[m][ks] = *(const bf16x8*)(P + (size_t)rowm[m] * INP + C_CKV + 32 * ks + 8 * fq); }
;             {
;                 f32x4 acc[2][4];
; #pragma unroll
;                 for (int m = 0; m < 2; ++m)
; #pragma unroll
;                     for (int n = 0; n < 4; ++n) acc[m][n] = (f32x4){0.f, 0.f, 0.f, 0.f};
; #pragma unroll
;                 for (int ks = 0; ks < 8; ++ks)
; #pragma unroll
;                     for (int n = 0; n < 4; ++n) { const bf16x8 bw = *(const LAS bf16x8*)(wl + (16 * n + fr) * WKS + 32 * ks + 8 * fq);
;                         acc[0][n] = MFMA16(bw, af[0][ks], acc[0][n]); acc[1][n] = MFMA16(bw, af[1][ks], acc[1][n]); }
.LBB0_524:
	v_add_u32_e32 v177, 1, v159
	v_cmp_gt_i32_e32 vcc, s12, v177
	v_add_u32_e32 v126, v158, v161
	v_ashrrev_i32_e32 v127, 31, v126
	v_cndmask_b32_e32 v0, v159, v177, vcc
	v_lshlrev_b32_e32 v178, 4, v0
	v_or_b32_e32 v120, v178, v158
	v_lshl_add_u64 v[22:23], v[126:127], 2, s[42:43]
	v_mov_b64_e32 v[26:27], s[40:41]
	global_load_dword v127, v[22:23], off
	v_mad_i64_i32 v[22:23], s[4:5], v126, s89, v[26:27]
	v_lshlrev_b32_e32 v0, 1, v115
	v_ashrrev_i32_e32 v121, 31, v120
	v_lshl_add_u64 v[24:25], v[22:23], 0, v[0:1]
	v_lshl_add_u64 v[34:35], v[120:121], 2, s[42:43]
	v_mad_i64_i32 v[22:23], s[4:5], v120, s89, v[26:27]
	global_load_dwordx2 v[130:131], v[24:25], off offset:1280
	global_load_dwordx2 v[128:129], v[24:25], off offset:1312
	global_load_dword v121, v[34:35], off
	v_lshl_add_u64 v[34:35], v[22:23], 0, v[0:1]
	v_and_b32_e32 v0, 3, v163
	v_bfe_u32 v226, v163, 2, 4
	global_load_dwordx2 v[124:125], v[34:35], off offset:1280
	global_load_dwordx2 v[122:123], v[34:35], off offset:1312
	v_lshlrev_b32_e32 v0, 4, v0
	v_and_b32_e32 v227, -16, v126
	v_lshl_add_u64 v[28:29], v[26:27], 0, v[0:1]
	v_add_u32_e32 v227, v227, v226
	v_add_u32_e32 v226, v178, v226
	v_mad_i64_i32 v[22:23], s[4:5], v227, s89, v[28:29]
	v_mad_i64_i32 v[26:27], s[4:5], v226, s89, v[28:29]
	global_load_dwordx4 v[78:81], v[22:23], off offset:768
	global_load_dwordx4 v[82:85], v[26:27], off offset:768
	global_load_dwordx4 v[66:69], v[22:23], off offset:832
	global_load_dwordx4 v[74:77], v[26:27], off offset:832
	global_load_dwordx4 v[62:65], v[22:23], off offset:896
	global_load_dwordx4 v[70:73], v[26:27], off offset:896
	global_load_dwordx4 v[50:53], v[22:23], off offset:960
	global_load_dwordx4 v[58:61], v[26:27], off offset:960
	global_load_dwordx4 v[46:49], v[22:23], off offset:1024
	global_load_dwordx4 v[54:57], v[26:27], off offset:1024
	global_load_dwordx4 v[38:41], v[22:23], off offset:1088
	global_load_dwordx4 v[42:45], v[26:27], off offset:1088
	global_load_dwordx4 v[30:33], v[22:23], off offset:1152
	global_load_dwordx4 v[34:37], v[26:27], off offset:1152
	s_nop 0
	global_load_dwordx4 v[22:25], v[22:23], off offset:1216
	global_load_dwordx4 v[26:29], v[26:27], off offset:1216
	s_waitcnt vmcnt(15)
	ds_write_b128 v242, v[78:81]
	ds_read_b128 v[78:81], v243
	s_waitcnt vmcnt(14)
	ds_write_b128 v242, v[82:85] offset:1024
	ds_read_b128 v[82:85], v243 offset:1024
	s_waitcnt vmcnt(13)
	ds_write_b128 v242, v[66:69] offset:2048
	ds_read_b128 v[66:69], v243 offset:2048
	s_waitcnt vmcnt(12)
	ds_write_b128 v242, v[74:77]
	ds_read_b128 v[74:77], v243
	ds_read_b128 v[230:233], v164 offset:0
	ds_read_b128 v[234:237], v164 offset:8448
	ds_read_b128 v[238:241], v164 offset:16896
	ds_read_b128 v[180:183], v164 offset:25344
	s_waitcnt lgkmcnt(3)
	v_mfma_f32_16x16x32_bf16 v[188:191], v[230:233], v[78:81], 0
	v_fmamk_f32 v0, v127, 0x3b800000, v140
	v_rsq_f32_e32 v0, v0
	v_mfma_f32_16x16x32_bf16 v[98:101], v[230:233], v[82:85], 0
	ds_read_b128 v[230:233], v164 offset:64
	s_waitcnt lgkmcnt(3)
	v_mfma_f32_16x16x32_bf16 v[192:195], v[234:237], v[78:81], 0
	v_mfma_f32_16x16x32_bf16 v[86:89], v[234:237], v[82:85], 0
	ds_read_b128 v[234:237], v164 offset:8512
	s_waitcnt vmcnt(11)
	ds_write_b128 v242, v[62:65] offset:1024
	ds_read_b128 v[62:65], v243 offset:1024
	s_waitcnt vmcnt(10)
	ds_write_b128 v242, v[70:73] offset:2048
	ds_read_b128 v[70:73], v243 offset:2048
	s_waitcnt lgkmcnt(7)
	v_mfma_f32_16x16x32_bf16 v[196:199], v[238:241], v[78:81], 0
	v_mfma_f32_16x16x32_bf16 v[94:97], v[238:241], v[82:85], 0
	ds_read_b128 v[238:241], v164 offset:16960
	s_waitcnt lgkmcnt(7)
	v_mfma_f32_16x16x32_bf16 v[184:187], v[180:183], v[78:81], 0
	v_mfma_f32_16x16x32_bf16 v[90:93], v[180:183], v[82:85], 0
	ds_read_b128 v[180:183], v164 offset:25408
	s_waitcnt lgkmcnt(7)
	v_mfma_f32_16x16x32_bf16 v[188:191], v[230:233], v[66:69], v[188:191]
	v_mfma_f32_16x16x32_bf16 v[98:101], v[230:233], v[74:77], v[98:101]
	ds_read_b128 v[230:233], v164 offset:128
	s_waitcnt lgkmcnt(7)
	v_mfma_f32_16x16x32_bf16 v[192:195], v[234:237], v[66:69], v[192:195]
	v_mfma_f32_16x16x32_bf16 v[86:89], v[234:237], v[74:77], v[86:89]
	ds_read_b128 v[234:237], v164 offset:8576
	s_waitcnt vmcnt(9)
	ds_write_b128 v242, v[50:53]
	ds_read_b128 v[50:53], v243
	s_waitcnt vmcnt(8)
	ds_write_b128 v242, v[58:61] offset:1024
	ds_read_b128 v[58:61], v243 offset:1024
	s_waitcnt lgkmcnt(7)
	v_mfma_f32_16x16x32_bf16 v[196:199], v[238:241], v[66:69], v[196:199]
	v_mfma_f32_16x16x32_bf16 v[94:97], v[238:241], v[74:77], v[94:97]
	ds_read_b128 v[238:241], v164 offset:17024
	s_waitcnt lgkmcnt(7)
	v_mfma_f32_16x16x32_bf16 v[184:187], v[180:183], v[66:69], v[184:187]
	v_mfma_f32_16x16x32_bf16 v[90:93], v[180:183], v[74:77], v[90:93]
	ds_read_b128 v[180:183], v164 offset:25472
	s_waitcnt lgkmcnt(7)
	v_mfma_f32_16x16x32_bf16 v[188:191], v[230:233], v[62:65], v[188:191]
	v_mfma_f32_16x16x32_bf16 v[98:101], v[230:233], v[70:73], v[98:101]
	ds_read_b128 v[230:233], v164 offset:192
	s_waitcnt lgkmcnt(7)
	v_mfma_f32_16x16x32_bf16 v[192:195], v[234:237], v[62:65], v[192:195]
	v_mfma_f32_16x16x32_bf16 v[86:89], v[234:237], v[70:73], v[86:89]
	ds_read_b128 v[234:237], v164 offset:8640
	s_waitcnt vmcnt(7)
	ds_write_b128 v242, v[46:49] offset:2048
	ds_read_b128 v[46:49], v243 offset:2048
	s_waitcnt vmcnt(6)
	ds_write_b128 v242, v[54:57]
	ds_read_b128 v[54:57], v243
	s_waitcnt lgkmcnt(7)
	v_mfma_f32_16x16x32_bf16 v[196:199], v[238:241], v[62:65], v[196:199]
	v_mfma_f32_16x16x32_bf16 v[94:97], v[238:241], v[70:73], v[94:97]
	ds_read_b128 v[238:241], v164 offset:17088
	s_waitcnt lgkmcnt(7)
; #define LAS __attribute__((address_space(3)))
; #define MFMA16(a, b, c) __builtin_amdgcn_mfma_f32_16x16x32_bf16((a), (b), (c), 0, 0, 0)
; __device__ __forceinline__ void qkv_head_unit(const Params& p, LAS unsigned char* lds, int h, int blk_begin, int blk_end) {
;     ...
;                 for (int ks = 0; ks < 8; ++ks)
; #pragma unroll
;                     for (int n = 0; n < 4; ++n) { const bf16x8 bw = *(const LAS bf16x8*)(wl + (16 * n + fr) * WKS + 32 * ks + 8 * fq);
;                         acc[0][n] = MFMA16(bw, af[0][ks], acc[0][n]); acc[1][n] = MFMA16(bw, af[1][ks], acc[1][n]); }
	v_mfma_f32_16x16x32_bf16 v[184:187], v[180:183], v[62:65], v[184:187]
	v_mfma_f32_16x16x32_bf16 v[90:93], v[180:183], v[70:73], v[90:93]
	ds_read_b128 v[180:183], v164 offset:25536
	s_waitcnt lgkmcnt(7)
	v_mfma_f32_16x16x32_bf16 v[188:191], v[230:233], v[50:53], v[188:191]
	v_mfma_f32_16x16x32_bf16 v[98:101], v[230:233], v[58:61], v[98:101]
	ds_read_b128 v[230:233], v164 offset:256
	s_waitcnt lgkmcnt(7)
	v_mfma_f32_16x16x32_bf16 v[192:195], v[234:237], v[50:53], v[192:195]
	v_mfma_f32_16x16x32_bf16 v[86:89], v[234:237], v[58:61], v[86:89]
	ds_read_b128 v[234:237], v164 offset:8704
	s_waitcnt vmcnt(5)
	ds_write_b128 v242, v[38:41] offset:1024
	ds_read_b128 v[38:41], v243 offset:1024
	s_waitcnt vmcnt(4)
	ds_write_b128 v242, v[42:45] offset:2048
	ds_read_b128 v[42:45], v243 offset:2048
	s_waitcnt lgkmcnt(7)
	v_mfma_f32_16x16x32_bf16 v[196:199], v[238:241], v[50:53], v[196:199]
	v_mfma_f32_16x16x32_bf16 v[94:97], v[238:241], v[58:61], v[94:97]
	ds_read_b128 v[238:241], v164 offset:17152
	s_waitcnt lgkmcnt(7)
	v_mfma_f32_16x16x32_bf16 v[184:187], v[180:183], v[50:53], v[184:187]
	v_mfma_f32_16x16x32_bf16 v[90:93], v[180:183], v[58:61], v[90:93]
	ds_read_b128 v[180:183], v164 offset:25600
	s_waitcnt lgkmcnt(7)
	v_mfma_f32_16x16x32_bf16 v[188:191], v[230:233], v[46:49], v[188:191]
	v_mfma_f32_16x16x32_bf16 v[98:101], v[230:233], v[54:57], v[98:101]
	ds_read_b128 v[230:233], v164 offset:320
	s_waitcnt lgkmcnt(7)
	v_mfma_f32_16x16x32_bf16 v[192:195], v[234:237], v[46:49], v[192:195]
	v_mfma_f32_16x16x32_bf16 v[86:89], v[234:237], v[54:57], v[86:89]
	ds_read_b128 v[234:237], v164 offset:8768
	s_waitcnt vmcnt(3)
	ds_write_b128 v242, v[30:33]
	ds_read_b128 v[30:33], v243
	s_waitcnt vmcnt(2)
	ds_write_b128 v242, v[34:37] offset:1024
	ds_read_b128 v[34:37], v243 offset:1024
	s_waitcnt lgkmcnt(7)
	v_mfma_f32_16x16x32_bf16 v[196:199], v[238:241], v[46:49], v[196:199]
	v_mfma_f32_16x16x32_bf16 v[94:97], v[238:241], v[54:57], v[94:97]
	ds_read_b128 v[238:241], v164 offset:17216
	s_waitcnt lgkmcnt(7)
	v_mfma_f32_16x16x32_bf16 v[184:187], v[180:183], v[46:49], v[184:187]
	v_mfma_f32_16x16x32_bf16 v[90:93], v[180:183], v[54:57], v[90:93]
	ds_read_b128 v[180:183], v164 offset:25664
	s_waitcnt lgkmcnt(7)
	v_mfma_f32_16x16x32_bf16 v[188:191], v[230:233], v[38:41], v[188:191]
	v_mfma_f32_16x16x32_bf16 v[98:101], v[230:233], v[42:45], v[98:101]
	ds_read_b128 v[230:233], v164 offset:384
	s_waitcnt lgkmcnt(7)
	v_mfma_f32_16x16x32_bf16 v[192:195], v[234:237], v[38:41], v[192:195]
	v_mfma_f32_16x16x32_bf16 v[86:89], v[234:237], v[42:45], v[86:89]
	ds_read_b128 v[234:237], v164 offset:8832
	s_waitcnt vmcnt(1)
	ds_write_b128 v242, v[22:25] offset:2048
	ds_read_b128 v[22:25], v243 offset:2048
	s_waitcnt vmcnt(0)
	ds_write_b128 v242, v[26:29]
	ds_read_b128 v[26:29], v243
	s_waitcnt lgkmcnt(7)
	v_mfma_f32_16x16x32_bf16 v[196:199], v[238:241], v[38:41], v[196:199]
	v_mfma_f32_16x16x32_bf16 v[94:97], v[238:241], v[42:45], v[94:97]
	ds_read_b128 v[238:241], v164 offset:17280
	s_waitcnt lgkmcnt(7)
	v_mfma_f32_16x16x32_bf16 v[184:187], v[180:183], v[38:41], v[184:187]
	v_mfma_f32_16x16x32_bf16 v[90:93], v[180:183], v[42:45], v[90:93]
	ds_read_b128 v[180:183], v164 offset:25728
	s_waitcnt lgkmcnt(7)
	v_mfma_f32_16x16x32_bf16 v[188:191], v[230:233], v[30:33], v[188:191]
	v_mfma_f32_16x16x32_bf16 v[98:101], v[230:233], v[34:37], v[98:101]
	ds_read_b128 v[230:233], v164 offset:448
	s_waitcnt lgkmcnt(7)
	v_mfma_f32_16x16x32_bf16 v[192:195], v[234:237], v[30:33], v[192:195]
	v_mfma_f32_16x16x32_bf16 v[86:89], v[234:237], v[34:37], v[86:89]
	ds_read_b128 v[234:237], v164 offset:8896
	s_waitcnt lgkmcnt(3)
	v_mfma_f32_16x16x32_bf16 v[196:199], v[238:241], v[30:33], v[196:199]
	v_mfma_f32_16x16x32_bf16 v[94:97], v[238:241], v[34:37], v[94:97]
	ds_read_b128 v[238:241], v164 offset:17344
	s_waitcnt lgkmcnt(3)
	v_mfma_f32_16x16x32_bf16 v[184:187], v[180:183], v[30:33], v[184:187]
	v_mfma_f32_16x16x32_bf16 v[90:93], v[180:183], v[34:37], v[90:93]
	ds_read_b128 v[180:183], v164 offset:25792
	s_waitcnt lgkmcnt(3)
	v_mfma_f32_16x16x32_bf16 v[188:191], v[230:233], v[22:25], v[188:191]
	v_mfma_f32_16x16x32_bf16 v[98:101], v[230:233], v[26:29], v[98:101]
	s_waitcnt lgkmcnt(2)
	v_mfma_f32_16x16x32_bf16 v[192:195], v[234:237], v[22:25], v[192:195]
	v_mfma_f32_16x16x32_bf16 v[86:89], v[234:237], v[26:29], v[86:89]
	s_waitcnt lgkmcnt(1)
	v_mfma_f32_16x16x32_bf16 v[196:199], v[238:241], v[22:25], v[196:199]
	v_mfma_f32_16x16x32_bf16 v[94:97], v[238:241], v[26:29], v[94:97]
	s_waitcnt lgkmcnt(0)
; #define LAS __attribute__((address_space(3)))
; __device__ __forceinline__ unsigned cvt_pk(float lo, float hi) { unsigned r; asm("v_cvt_pk_bf16_f32 %0, %1, %2" : "=v"(r) : "v"(lo), "v"(hi)); return r; }
; __device__ __forceinline__ float frsq(float x) { return __builtin_amdgcn_rsqf(x); }
; __device__ __forceinline__ void qkv_head_unit(const Params& p, LAS unsigned char* lds, int h, int blk_begin, int blk_end) {
;     ...
;                         acc[0][n] = MFMA16(bw, af[0][ks], acc[0][n]); acc[1][n] = MFMA16(bw, af[1][ks], acc[1][n]); }
; #pragma unroll
;                 for (int mi = 0; mi < 2; ++mi) {
;                     const bool valid = (mi == 0) || two;
;                     const int t = rowm[mi] % TT;
;                     const float sc = frsq(ssv[mi] * (1.0f / 256.0f) + EPS);
;                     const u32x2 k1 = k1v[mi], k2 = k2v[mi];
;                     f32x4 kr1 = (f32x4){bflo(k1.x), bfhi(k1.x), bflo(k1.y), bfhi(k1.y)}, kr2 = (f32x4){bflo(k2.x), bfhi(k2.x), bflo(k2.y), bfhi(k2.y)};
;                     float ssq = (kr1[0] * kr1[0] + kr1[1] * kr1[1]) + (kr1[2] * kr1[2] + kr1[3] * kr1[3]) + (kr2[0] * kr2[0] + kr2[1] * kr2[1]) + (kr2[2] * kr2[2] + kr2[3] * kr2[3]);
; #pragma unroll
;                     for (int n = 0; n < 4; ++n) { acc[mi][n] *= sc; ssq += (acc[mi][n][0] * acc[mi][n][0] + acc[mi][n][1] * acc[mi][n][1]) + (acc[mi][n][2] * acc[mi][n][2] + acc[mi][n][3] * acc[mi][n][3]); }
;                     ssq += __shfl_xor(ssq, 16); ssq += __shfl_xor(ssq, 32);
;                     const float rk = frsq(ssq * (1.0f / 96.0f) + EPS);
;                     LAS bf16_t* dstk = stg + fr * 104 + 4 * fq;
; #pragma unroll
;                     for (int n = 0; n < 4; ++n) { const f32x4 v = acc[mi][n] * rk * gvv[n]; u32x2 wv; wv.x = cvt_pk(v[0], v[1]); wv.y = cvt_pk(v[2], v[3]); *(LAS u32x2*)(dstk + 16 * n) = wv; }
;                     { kr1 = kr1 * rk * gvv[4]; kr2 = kr2 * rk * gvv[5];
;                       f32x4 o1, o2;
; #pragma unroll
;                       for (int i = 0; i < 4; ++i) { float sn, cs; sincos_rr((float)t * frq[i], sn, cs);
;                           o1[i] = kr1[i] * cs - kr2[i] * sn; o2[i] = kr1[i] * sn + kr2[i] * cs; }
;                       u32x2 wv; wv.x = cvt_pk(o1[0], o1[1]); wv.y = cvt_pk(o1[2], o1[3]); *(LAS u32x2*)(dstk + 64) = wv; wv.x = cvt_pk(o2[0], o2[1]); wv.y = cvt_pk(o2[2], o2[3]); *(LAS u32x2*)(dstk + 80) = wv; }
	v_mfma_f32_16x16x32_bf16 v[184:187], v[180:183], v[22:25], v[184:187]
	v_mfma_f32_16x16x32_bf16 v[90:93], v[180:183], v[26:29], v[90:93]
	v_lshlrev_b32_e32 v137, 16, v131
	v_lshlrev_b32_e32 v136, 16, v130
	v_and_b32_e32 v131, 0xffff0000, v131
	v_and_b32_e32 v130, 0xffff0000, v130
	v_pk_mul_f32 v[138:139], v[130:131], v[130:131]
	v_lshlrev_b32_e32 v132, 16, v129
	v_and_b32_e32 v134, 0xffff0000, v129
	s_nop 7
	v_pk_mul_f32 v[196:197], v[0:1], v[196:197] op_sel_hi:[0,1]
	v_mul_f32_e64 v184, v0, v184
	v_mul_f32_e64 v185, v0, v185
	v_pk_mul_f32 v[186:187], v[0:1], v[186:187] op_sel_hi:[0,1]
	v_pk_fma_f32 v[180:181], v[136:137], v[136:137], v[138:139]
	v_and_b32_e32 v139, 0xffff0000, v128
	v_lshlrev_b32_e32 v138, 16, v128
	v_pk_mul_f32 v[128:129], v[0:1], v[190:191] op_sel_hi:[0,1]
	v_pk_mul_f32 v[182:183], v[0:1], v[188:189] op_sel_hi:[0,1]
	v_mul_f32_e32 v190, v139, v139
	v_mul_f32_e32 v127, v128, v128
	v_mul_f32_e32 v179, v129, v129
	v_mov_b32_e32 v135, v183
	v_pk_add_f32 v[180:181], v[180:181], v[180:181] op_sel:[0,1] op_sel_hi:[1,0]
	v_pk_fma_f32 v[190:191], v[138:139], v[138:139], v[190:191] op_sel_hi:[1,1,0]
	v_mov_b32_e32 v133, v182
	v_pk_mul_f32 v[188:189], v[134:135], v[134:135]
	v_mov_b32_e32 v181, v127
	v_mov_b32_e32 v191, v179
	v_pk_fma_f32 v[188:189], v[132:133], v[132:133], v[188:189]
	v_pk_add_f32 v[180:181], v[180:181], v[190:191]
	v_pk_mul_f32 v[190:191], v[0:1], v[192:193] op_sel_hi:[0,1]
	v_pk_add_f32 v[180:181], v[188:189], v[180:181]
	v_pk_mul_f32 v[188:189], v[0:1], v[194:195] op_sel_hi:[0,1]
	v_pk_mul_f32 v[192:193], v[188:189], v[188:189]
	v_pk_mul_f32 v[194:195], v[190:191], v[190:191]
	v_mul_f32_e32 v127, v184, v184
	v_pk_mov_b32 v[200:201], v[194:195], v[192:193] op_sel:[1,0]
	v_mov_b32_e32 v195, v193
	v_pk_add_f32 v[192:193], v[200:201], v[194:195]
	v_mul_f32_e32 v133, v185, v185
	v_pk_add_f32 v[180:181], v[180:181], v[180:181] op_sel:[0,1] op_sel_hi:[1,0]
	v_pk_add_f32 v[192:193], v[192:193], v[192:193] op_sel:[0,1] op_sel_hi:[1,0]
	v_pk_mul_f32 v[194:195], v[0:1], v[198:199] op_sel_hi:[0,1]
	v_mov_b32_e32 v181, v127
	v_mov_b32_e32 v193, v133
	v_pk_add_f32 v[180:181], v[180:181], v[192:193]
	v_mul_f32_e32 v192, v197, v197
	v_mul_f32_e32 v198, v195, v195
	v_mul_f32_e32 v135, v186, v186
	v_mul_f32_e32 v179, v187, v187
	v_pk_fma_f32 v[192:193], v[196:197], v[196:197], v[192:193] op_sel_hi:[1,1,0]
	v_pk_fma_f32 v[198:199], v[194:195], v[194:195], v[198:199] op_sel_hi:[1,1,0]
	v_mov_b32_e32 v193, v135
	v_mov_b32_e32 v199, v179
	v_pk_add_f32 v[192:193], v[192:193], v[198:199]
	s_nop 0
	v_pk_add_f32 v[180:181], v[180:181], v[192:193]
	s_nop 0
	v_add_f32_e32 v127, v180, v181
	ds_bpermute_b32 v133, v103, v127
	s_waitcnt lgkmcnt(0)
	v_add_f32_e32 v127, v127, v133
	ds_bpermute_b32 v133, v105, v127
	s_waitcnt lgkmcnt(0)
	v_add_f32_e32 v127, v127, v133
	v_fmamk_f32 v127, v127, 0x3c2aaaab, v140
	v_rsq_f32_e32 v180, v127
	v_add_u32_e32 v127, v160, v114
	v_mov_b32_e32 v133, v134
	v_pk_mul_f32 v[182:183], v[182:183], v[180:181] op_sel_hi:[1,0]
	v_pk_mul_f32 v[128:129], v[128:129], v[180:181] op_sel_hi:[1,0]
	v_pk_mul_f32 v[182:183], v[6:7], v[182:183]
	v_pk_mul_f32 v[128:129], v[8:9], v[128:129]
	v_cvt_pk_bf16_f32 v182, v182, v183
	v_pk_mul_f32 v[188:189], v[188:189], v[180:181] op_sel_hi:[1,0]
	v_cvt_pk_bf16_f32 v183, v128, v129
	v_pk_mul_f32 v[128:129], v[190:191], v[180:181] op_sel_hi:[1,0]
	v_pk_mul_f32 v[188:189], v[12:13], v[188:189]
	v_pk_mul_f32 v[128:129], v[10:11], v[128:129]
	v_pk_mul_f32 v[134:135], v[138:139], v[180:181] op_sel_hi:[1,0]
	v_cvt_pk_bf16_f32 v128, v128, v129
	v_cvt_pk_bf16_f32 v129, v188, v189
	ds_write2_b64 v127, v[182:183], v[128:129] offset1:4
	v_pk_mul_f32 v[128:129], v[196:197], v[180:181] op_sel_hi:[1,0]
	v_pk_mul_f32 v[182:183], v[194:195], v[180:181] op_sel_hi:[1,0]
	v_pk_mul_f32 v[128:129], v[14:15], v[128:129]
	v_pk_mul_f32 v[182:183], v[16:17], v[182:183]
	v_cvt_pk_bf16_f32 v128, v128, v129
	v_mov_b32_e32 v139, v134
	v_cvt_pk_bf16_f32 v129, v182, v183
	v_pk_mul_f32 v[182:183], v[184:185], v[180:181] op_sel_hi:[1,0]
	v_pk_mul_f32 v[184:185], v[186:187], v[180:181] op_sel_hi:[1,0]
	v_pk_mul_f32 v[182:183], v[18:19], v[182:183]
	v_pk_mul_f32 v[184:185], v[20:21], v[184:185]
	v_cvt_pk_bf16_f32 v182, v182, v183
	v_pk_mul_f32 v[132:133], v[132:133], v[180:181] op_sel_hi:[1,0]
	v_cvt_pk_bf16_f32 v183, v184, v185
	ds_write2_b64 v127, v[128:129], v[182:183] offset0:8 offset1:12
	v_mul_hi_i32 v128, v126, s90
	v_lshrrev_b32_e32 v129, 31, v128
	v_ashrrev_i32_e32 v128, 7, v128
	v_add_u32_e32 v128, v128, v129
	v_mul_lo_u32 v128, v128, s86
	v_sub_u32_e32 v126, v126, v128
	v_cvt_f32_i32_e32 v126, v126
	v_mov_b32_e32 v128, v137
	v_mov_b32_e32 v137, v130
	v_mov_b32_e32 v129, v131
	v_pk_mul_f32 v[130:131], v[180:181], v[136:137] op_sel_hi:[0,1]
	v_mul_f32_e32 v136, v154, v126
	v_mul_f32_e32 v137, 0.15915494, v136
	v_rndne_f32_e32 v137, v137
	v_fmac_f32_e32 v136, 0xc0c90fdb, v137
	v_fmac_f32_e32 v136, 0x343bbd2e, v137
	v_mul_f32_e32 v136, 0.15915494, v136
	v_sin_f32_e32 v137, v136
	v_cos_f32_e32 v136, v136
	v_mov_b32_e32 v138, v130
	v_mul_f32_e32 v130, v155, v126
	v_mul_f32_e32 v134, 0.15915494, v130
	v_pk_mul_f32 v[138:139], v[118:119], v[138:139]
	v_rndne_f32_e32 v134, v134
	v_pk_mul_f32 v[128:129], v[180:181], v[128:129] op_sel_hi:[0,1]
	v_pk_mul_f32 v[180:181], v[136:137], v[138:139]
	v_fmac_f32_e32 v130, 0xc0c90fdb, v134
	v_sub_f32_e32 v179, v180, v181
	v_mov_b32_e32 v180, v137
	v_mov_b32_e32 v181, v136
	v_fmac_f32_e32 v130, 0x343bbd2e, v134
	v_pk_mul_f32 v[136:137], v[180:181], v[138:139]
	v_mul_f32_e32 v130, 0.15915494, v130
	v_add_f32_e32 v138, v136, v137
	v_sin_f32_e32 v137, v130
	v_cos_f32_e32 v136, v130
; #define LAS __attribute__((address_space(3)))
; __device__ __forceinline__ void qkv_head_unit(const Params& p, LAS unsigned char* lds, int h, int blk_begin, int blk_end) {
;     ...
;                     const float sc = frsq(ssv[mi] * (1.0f / 256.0f) + EPS);
;                     const u32x2 k1 = k1v[mi], k2 = k2v[mi];
;                     f32x4 kr1 = (f32x4){bflo(k1.x), bfhi(k1.x), bflo(k1.y), bfhi(k1.y)}, kr2 = (f32x4){bflo(k2.x), bfhi(k2.x), bflo(k2.y), bfhi(k2.y)};
;                     float ssq = (kr1[0] * kr1[0] + kr1[1] * kr1[1]) + (kr1[2] * kr1[2] + kr1[3] * kr1[3]) + (kr2[0] * kr2[0] + kr2[1] * kr2[1]) + (kr2[2] * kr2[2] + kr2[3] * kr2[3]);
; #pragma unroll
;                     for (int n = 0; n < 4; ++n) { acc[mi][n] *= sc; ssq += (acc[mi][n][0] * acc[mi][n][0] + acc[mi][n][1] * acc[mi][n][1]) + (acc[mi][n][2] * acc[mi][n][2] + acc[mi][n][3] * acc[mi][n][3]); }
;                     ssq += __shfl_xor(ssq, 16); ssq += __shfl_xor(ssq, 32);
;                     const float rk = frsq(ssq * (1.0f / 96.0f) + EPS);
;                     LAS bf16_t* dstk = stg + fr * 104 + 4 * fq;
; #pragma unroll
;                     for (int n = 0; n < 4; ++n) { const f32x4 v = acc[mi][n] * rk * gvv[n]; u32x2 wv; wv.x = cvt_pk(v[0], v[1]); wv.y = cvt_pk(v[2], v[3]); *(LAS u32x2*)(dstk + 16 * n) = wv; }
;                     { kr1 = kr1 * rk * gvv[4]; kr2 = kr2 * rk * gvv[5];
;                       f32x4 o1, o2;
; #pragma unroll
;                       for (int i = 0; i < 4; ++i) { float sn, cs; sincos_rr((float)t * frq[i], sn, cs);
;                           o1[i] = kr1[i] * cs - kr2[i] * sn; o2[i] = kr1[i] * sn + kr2[i] * cs; }
;                       u32x2 wv; wv.x = cvt_pk(o1[0], o1[1]); wv.y = cvt_pk(o1[2], o1[3]); *(LAS u32x2*)(dstk + 64) = wv; wv.x = cvt_pk(o2[0], o2[1]); wv.y = cvt_pk(o2[2], o2[3]); *(LAS u32x2*)(dstk + 80) = wv; }
;                     asm volatile("s_waitcnt lgkmcnt(0)" ::: "memory");
; #pragma unroll
;                     for (int j = 0; j < 3; ++j) { const int c = lane + 64 * j, rw = c / 12, cc = c % 12; const int row2 = 16 * (mi ? blk1 : pb) + rw, b2 = row2 / TT, t2 = row2 % TT;
;                         const u32x4 v = *(const LAS u32x4*)(stg + rw * 104 + 8 * cc);
;                         if (valid) __builtin_nontemporal_store(v, (u32x4*)(Kb + (((size_t)(b2 * NH + h)) * TKP + t2) * QKH + 8 * cc)); }
	v_mov_b32_e32 v134, v131
	v_pk_mul_f32 v[130:131], v[2:3], v[134:135]
	s_nop 0
	v_pk_mul_f32 v[134:135], v[136:137], v[130:131]
	s_nop 0
	v_sub_f32_e32 v139, v134, v135
	v_mov_b32_e32 v134, v137
	v_mov_b32_e32 v135, v136
	v_pk_mul_f32 v[130:131], v[134:135], v[130:131]
	v_mov_b32_e32 v134, v128
	v_add_f32_e32 v180, v130, v131
	v_mul_f32_e32 v130, v156, v126
	v_mul_f32_e32 v131, 0.15915494, v130
	v_rndne_f32_e32 v131, v131
	v_fmac_f32_e32 v130, 0xc0c90fdb, v131
	v_fmac_f32_e32 v130, 0x343bbd2e, v131
	v_mul_f32_e32 v130, 0.15915494, v130
	v_sin_f32_e32 v131, v130
	v_cos_f32_e32 v130, v130
	v_mul_f32_e32 v126, v157, v126
	v_mov_b32_e32 v135, v132
	v_mul_f32_e32 v128, 0.15915494, v126
	v_pk_mul_f32 v[134:135], v[116:117], v[134:135]
	v_rndne_f32_e32 v128, v128
	v_pk_mul_f32 v[136:137], v[130:131], v[134:135]
	v_fmac_f32_e32 v126, 0xc0c90fdb, v128
	v_sub_f32_e32 v181, v136, v137
	v_mov_b32_e32 v136, v131
	v_mov_b32_e32 v137, v130
	v_fmac_f32_e32 v126, 0x343bbd2e, v128
	v_pk_mul_f32 v[130:131], v[136:137], v[134:135]
	v_mul_f32_e32 v126, 0.15915494, v126
	v_add_f32_e32 v134, v130, v131
	v_sin_f32_e32 v131, v126
	v_cos_f32_e32 v130, v126
	v_mov_b32_e32 v132, v129
	v_pk_mul_f32 v[128:129], v[4:5], v[132:133]
	s_nop 0
	v_pk_mul_f32 v[132:133], v[130:131], v[128:129]
	s_nop 0
	v_sub_f32_e32 v126, v132, v133
	v_mov_b32_e32 v132, v131
	v_mov_b32_e32 v133, v130
	v_pk_mul_f32 v[128:129], v[132:133], v[128:129]
	v_cvt_pk_bf16_f32 v130, v138, v180
	s_nop 0
	v_add_f32_e32 v131, v128, v129
	v_cvt_pk_bf16_f32 v129, v181, v126
	v_add_u32_e32 v126, v107, v161
	v_mul_hi_i32 v132, v126, s90
	v_lshrrev_b32_e32 v133, 31, v132
	v_ashrrev_i32_e32 v132, 7, v132
	v_add_u32_e32 v133, v132, v133
	v_mul_i32_i24_e32 v132, 0x810, v133
	v_sub_u32_e32 v132, v126, v132
	v_lshl_or_b32 v126, v133, 3, s16
	v_cvt_pk_bf16_f32 v131, v134, v131
	v_mul_hi_i32_i24_e32 v135, 0x840, v126
	v_mul_i32_i24_e32 v134, 0x840, v126
	v_ashrrev_i32_e32 v133, 31, v132
	v_lshl_add_u64 v[132:133], v[134:135], 0, v[132:133]
	v_mad_u64_u32 v[134:135], s[4:5], v132, s91, v[108:109]
	v_cvt_pk_bf16_f32 v128, v179, v139
	ds_write2_b64 v127, v[128:129], v[130:131] offset0:16 offset1:20
	v_mov_b32_e32 v126, v135
	s_waitcnt lgkmcnt(0)
	v_mad_u64_u32 v[132:133], s[4:5], v133, s91, v[126:127]
	v_add_u32_e32 v126, v170, v161
	ds_read_b128 v[128:131], v173
	v_mov_b32_e32 v135, v132
	v_mul_hi_i32 v132, v126, s90
	v_lshrrev_b32_e32 v133, 31, v132
	v_ashrrev_i32_e32 v132, 7, v132
	v_add_u32_e32 v133, v132, v133
	v_mul_i32_i24_e32 v132, 0x810, v133
	v_sub_u32_e32 v132, v126, v132
	v_lshl_or_b32 v126, v133, 3, s16
	s_waitcnt lgkmcnt(0)
	global_store_dwordx4 v[134:135], v[128:131], off nt
	v_mul_hi_i32_i24_e32 v135, 0x840, v126
	v_mul_i32_i24_e32 v134, 0x840, v126
	v_ashrrev_i32_e32 v133, 31, v132
	v_lshl_add_u64 v[132:133], v[134:135], 0, v[132:133]
	v_mad_u64_u32 v[134:135], s[4:5], v132, s91, v[110:111]
	v_mov_b32_e32 v126, v135
	v_mad_u64_u32 v[132:133], s[4:5], v133, s91, v[126:127]
	v_add_u32_e32 v126, v171, v161
	ds_read_b128 v[128:131], v174
	v_mov_b32_e32 v135, v132
	v_mul_hi_i32 v132, v126, s90
	v_lshrrev_b32_e32 v133, 31, v132
	v_ashrrev_i32_e32 v132, 7, v132
	v_add_u32_e32 v133, v132, v133
	v_mul_i32_i24_e32 v132, 0x810, v133
	v_sub_u32_e32 v132, v126, v132
	v_lshl_or_b32 v126, v133, 3, s16
	s_waitcnt lgkmcnt(0)
	global_store_dwordx4 v[134:135], v[128:131], off nt
	v_mul_hi_i32_i24_e32 v135, 0x840, v126
	v_mul_i32_i24_e32 v134, 0x840, v126
	v_ashrrev_i32_e32 v133, 31, v132
	ds_read_b128 v[128:131], v175
	v_lshl_add_u64 v[132:133], v[134:135], 0, v[132:133]
	v_mad_u64_u32 v[134:135], s[4:5], v132, s91, v[112:113]
	v_mov_b32_e32 v126, v135
	v_mad_u64_u32 v[132:133], s[4:5], v133, s91, v[126:127]
	v_mov_b32_e32 v135, v132
	s_waitcnt lgkmcnt(0)
	global_store_dwordx4 v[134:135], v[128:131], off nt
	s_waitcnt lgkmcnt(0)
	v_fmamk_f32 v121, v121, 0x3b800000, v140
	v_rsq_f32_e32 v126, v121
	v_lshlrev_b32_e32 v133, 16, v125
	v_lshlrev_b32_e32 v132, 16, v124
	v_and_b32_e32 v125, 0xffff0000, v125
	v_and_b32_e32 v124, 0xffff0000, v124
	v_pk_mul_f32 v[134:135], v[124:125], v[124:125]
	v_and_b32_e32 v137, 0xffff0000, v122
	v_pk_fma_f32 v[134:135], v[132:133], v[132:133], v[134:135]
	v_lshlrev_b32_e32 v136, 16, v122
	v_pk_mul_f32 v[98:99], v[126:127], v[98:99] op_sel_hi:[0,1]
	v_pk_mul_f32 v[100:101], v[126:127], v[100:101] op_sel_hi:[0,1]
	v_mul_f32_e32 v138, v137, v137
	v_and_b32_e32 v130, 0xffff0000, v123
	v_mul_f32_e32 v121, v100, v100
	v_mul_f32_e32 v179, v101, v101
	v_mov_b32_e32 v131, v99
	v_pk_add_f32 v[134:135], v[134:135], v[134:135] op_sel:[0,1] op_sel_hi:[1,0]
	v_pk_fma_f32 v[138:139], v[136:137], v[136:137], v[138:139] op_sel_hi:[1,1,0]
	v_lshlrev_b32_e32 v128, 16, v123
	v_mov_b32_e32 v129, v98
	v_pk_mul_f32 v[122:123], v[130:131], v[130:131]
	v_mov_b32_e32 v135, v121
	v_mov_b32_e32 v139, v179
	v_pk_fma_f32 v[122:123], v[128:129], v[128:129], v[122:123]
	v_pk_add_f32 v[134:135], v[134:135], v[138:139]
	v_pk_mul_f32 v[88:89], v[126:127], v[88:89] op_sel_hi:[0,1]
	v_pk_mul_f32 v[86:87], v[126:127], v[86:87] op_sel_hi:[0,1]
	v_pk_add_f32 v[122:123], v[122:123], v[134:135]
	v_pk_mul_f32 v[134:135], v[86:87], v[86:87]
	v_pk_mul_f32 v[138:139], v[88:89], v[88:89]
	v_pk_mul_f32 v[90:91], v[126:127], v[90:91] op_sel_hi:[0,1]
	v_pk_mov_b32 v[180:181], v[134:135], v[138:139] op_sel:[1,0]
	v_mov_b32_e32 v135, v139
	v_pk_add_f32 v[134:135], v[180:181], v[134:135]
	v_mul_f32_e32 v121, v90, v90
	v_mul_f32_e32 v129, v91, v91
	v_pk_add_f32 v[122:123], v[122:123], v[122:123] op_sel:[0,1] op_sel_hi:[1,0]
	v_pk_add_f32 v[134:135], v[134:135], v[134:135] op_sel:[0,1] op_sel_hi:[1,0]
	v_pk_mul_f32 v[96:97], v[126:127], v[96:97] op_sel_hi:[0,1]
	v_pk_mul_f32 v[94:95], v[126:127], v[94:95] op_sel_hi:[0,1]
	v_mov_b32_e32 v123, v121
	v_mov_b32_e32 v135, v129
	v_pk_mul_f32 v[92:93], v[126:127], v[92:93] op_sel_hi:[0,1]
	v_pk_add_f32 v[122:123], v[122:123], v[134:135]
	v_mul_f32_e32 v134, v95, v95
	v_mul_f32_e32 v138, v97, v97
	v_mul_f32_e32 v131, v92, v92
	v_mul_f32_e32 v179, v93, v93
	v_pk_fma_f32 v[134:135], v[94:95], v[94:95], v[134:135] op_sel_hi:[1,1,0]
	v_pk_fma_f32 v[138:139], v[96:97], v[96:97], v[138:139] op_sel_hi:[1,1,0]
	v_mov_b32_e32 v135, v131
	v_mov_b32_e32 v139, v179
	v_pk_add_f32 v[134:135], v[134:135], v[138:139]
	v_mov_b32_e32 v129, v130
	v_pk_add_f32 v[122:123], v[122:123], v[134:135]
	s_nop 0
	v_add_f32_e32 v121, v122, v123
	ds_bpermute_b32 v122, v103, v121
	s_waitcnt lgkmcnt(0)
; #define LAS __attribute__((address_space(3)))
; __device__ __forceinline__ unsigned cvt_pk(float lo, float hi) { unsigned r; asm("v_cvt_pk_bf16_f32 %0, %1, %2" : "=v"(r) : "v"(lo), "v"(hi)); return r; }
; __device__ __forceinline__ float frsq(float x) { return __builtin_amdgcn_rsqf(x); }
; __device__ __forceinline__ void qkv_head_unit(const Params& p, LAS unsigned char* lds, int h, int blk_begin, int blk_end) {
;     ...
;                     ssq += __shfl_xor(ssq, 16); ssq += __shfl_xor(ssq, 32);
;                     const float rk = frsq(ssq * (1.0f / 96.0f) + EPS);
;                     LAS bf16_t* dstk = stg + fr * 104 + 4 * fq;
; #pragma unroll
;                     for (int n = 0; n < 4; ++n) { const f32x4 v = acc[mi][n] * rk * gvv[n]; u32x2 wv; wv.x = cvt_pk(v[0], v[1]); wv.y = cvt_pk(v[2], v[3]); *(LAS u32x2*)(dstk + 16 * n) = wv; }
;                     { kr1 = kr1 * rk * gvv[4]; kr2 = kr2 * rk * gvv[5];
;                       f32x4 o1, o2;
; #pragma unroll
;                       for (int i = 0; i < 4; ++i) { float sn, cs; sincos_rr((float)t * frq[i], sn, cs);
;                           o1[i] = kr1[i] * cs - kr2[i] * sn; o2[i] = kr1[i] * sn + kr2[i] * cs; }
;                       u32x2 wv; wv.x = cvt_pk(o1[0], o1[1]); wv.y = cvt_pk(o1[2], o1[3]); *(LAS u32x2*)(dstk + 64) = wv; wv.x = cvt_pk(o2[0], o2[1]); wv.y = cvt_pk(o2[2], o2[3]); *(LAS u32x2*)(dstk + 80) = wv; }
;                     asm volatile("s_waitcnt lgkmcnt(0)" ::: "memory");
; #pragma unroll
;                     for (int j = 0; j < 3; ++j) { const int c = lane + 64 * j, rw = c / 12, cc = c % 12; const int row2 = 16 * (mi ? blk1 : pb) + rw, b2 = row2 / TT, t2 = row2 % TT;
;                         const u32x4 v = *(const LAS u32x4*)(stg + rw * 104 + 8 * cc);
;                         if (valid) __builtin_nontemporal_store(v, (u32x4*)(Kb + (((size_t)(b2 * NH + h)) * TKP + t2) * QKH + 8 * cc)); }
;                     asm volatile("s_waitcnt lgkmcnt(0)" ::: "memory"); __builtin_amdgcn_sched_barrier(0);
	v_add_f32_e32 v121, v121, v122
	ds_bpermute_b32 v122, v105, v121
	s_waitcnt lgkmcnt(0)
	v_add_f32_e32 v121, v121, v122
	v_fmamk_f32 v121, v121, 0x3c2aaaab, v140
	v_rsq_f32_e32 v122, v121
	s_nop 0
	v_pk_mul_f32 v[86:87], v[86:87], v[122:123] op_sel_hi:[1,0]
	v_pk_mul_f32 v[98:99], v[98:99], v[122:123] op_sel_hi:[1,0]
	v_pk_mul_f32 v[88:89], v[88:89], v[122:123] op_sel_hi:[1,0]
	v_pk_mul_f32 v[86:87], v[10:11], v[86:87]
	v_pk_mul_f32 v[100:101], v[100:101], v[122:123] op_sel_hi:[1,0]
	v_pk_mul_f32 v[98:99], v[6:7], v[98:99]
	v_pk_mul_f32 v[88:89], v[12:13], v[88:89]
	v_cvt_pk_bf16_f32 v86, v86, v87
	v_pk_mul_f32 v[100:101], v[8:9], v[100:101]
	v_cvt_pk_bf16_f32 v87, v88, v89
	v_cvt_pk_bf16_f32 v98, v98, v99
	v_pk_mul_f32 v[88:89], v[96:97], v[122:123] op_sel_hi:[1,0]
	v_cvt_pk_bf16_f32 v99, v100, v101
	ds_write2_b64 v127, v[98:99], v[86:87] offset1:4
	v_pk_mul_f32 v[86:87], v[94:95], v[122:123] op_sel_hi:[1,0]
	v_pk_mul_f32 v[88:89], v[16:17], v[88:89]
	v_pk_mul_f32 v[86:87], v[14:15], v[86:87]
	s_nop 0
	v_cvt_pk_bf16_f32 v86, v86, v87
	v_cvt_pk_bf16_f32 v87, v88, v89
	v_pk_mul_f32 v[88:89], v[90:91], v[122:123] op_sel_hi:[1,0]
	v_pk_mul_f32 v[90:91], v[92:93], v[122:123] op_sel_hi:[1,0]
	v_pk_mul_f32 v[88:89], v[18:19], v[88:89]
	v_pk_mul_f32 v[90:91], v[20:21], v[90:91]
	v_cvt_pk_bf16_f32 v88, v88, v89
	v_pk_mul_f32 v[92:93], v[136:137], v[122:123] op_sel_hi:[1,0]
	v_cvt_pk_bf16_f32 v89, v90, v91
	ds_write2_b64 v127, v[86:87], v[88:89] offset0:8 offset1:12
	v_mul_hi_i32 v86, v120, s90
	v_lshrrev_b32_e32 v87, 31, v86
	v_ashrrev_i32_e32 v86, 7, v86
	v_add_u32_e32 v86, v86, v87
	v_mul_lo_u32 v86, v86, s86
	v_sub_u32_e32 v90, v120, v86
	v_cvt_f32_i32_e32 v100, v90
	v_mov_b32_e32 v86, v133
	v_mov_b32_e32 v133, v124
	v_pk_mul_f32 v[88:89], v[122:123], v[132:133] op_sel_hi:[0,1]
	v_mul_f32_e32 v94, v154, v100
	v_mul_f32_e32 v95, 0.15915494, v94
	v_rndne_f32_e32 v95, v95
	v_fmac_f32_e32 v94, 0xc0c90fdb, v95
	v_fmac_f32_e32 v94, 0x343bbd2e, v95
	v_mul_f32_e32 v94, 0.15915494, v94
	v_sin_f32_e32 v95, v94
	v_cos_f32_e32 v94, v94
	v_mov_b32_e32 v96, v88
	v_mul_f32_e32 v88, v155, v100
	v_mov_b32_e32 v97, v92
	v_mul_f32_e32 v92, 0.15915494, v88
	v_rndne_f32_e32 v92, v92
	v_pk_mul_f32 v[96:97], v[118:119], v[96:97]
	v_fmac_f32_e32 v88, 0xc0c90fdb, v92
	v_pk_mul_f32 v[98:99], v[94:95], v[96:97]
	v_fmac_f32_e32 v88, 0x343bbd2e, v92
	v_sub_f32_e32 v101, v98, v99
	v_mov_b32_e32 v98, v95
	v_mov_b32_e32 v99, v94
	v_mul_f32_e32 v88, 0.15915494, v88
	v_pk_mul_f32 v[94:95], v[98:99], v[96:97]
	v_sin_f32_e32 v97, v88
	v_cos_f32_e32 v96, v88
	v_mov_b32_e32 v92, v89
	v_pk_mul_f32 v[88:89], v[2:3], v[92:93]
	v_mov_b32_e32 v87, v125
	v_pk_mul_f32 v[92:93], v[96:97], v[88:89]
	v_pk_mul_f32 v[86:87], v[122:123], v[86:87] op_sel_hi:[0,1]
	v_sub_f32_e32 v99, v92, v93
	v_mov_b32_e32 v92, v97
	v_mov_b32_e32 v93, v96
	v_pk_mul_f32 v[88:89], v[92:93], v[88:89]
	v_pk_mul_f32 v[90:91], v[128:129], v[122:123] op_sel_hi:[1,0]
	v_add_f32_e32 v96, v88, v89
	v_mul_f32_e32 v88, v156, v100
	v_mul_f32_e32 v89, 0.15915494, v88
	v_rndne_f32_e32 v89, v89
	v_fmac_f32_e32 v88, 0xc0c90fdb, v89
	v_fmac_f32_e32 v88, 0x343bbd2e, v89
	v_mul_f32_e32 v88, 0.15915494, v88
	v_sin_f32_e32 v89, v88
	v_cos_f32_e32 v88, v88
	v_mov_b32_e32 v92, v86
	v_mul_f32_e32 v86, v157, v100
	v_mov_b32_e32 v93, v90
	v_mul_f32_e32 v90, 0.15915494, v86
	v_rndne_f32_e32 v90, v90
	v_pk_mul_f32 v[92:93], v[116:117], v[92:93]
	v_fmac_f32_e32 v86, 0xc0c90fdb, v90
	v_add_f32_e32 v98, v94, v95
	v_pk_mul_f32 v[94:95], v[88:89], v[92:93]
	v_fmac_f32_e32 v86, 0x343bbd2e, v90
	v_sub_f32_e32 v97, v94, v95
	v_mov_b32_e32 v94, v89
	v_mov_b32_e32 v95, v88
	v_mul_f32_e32 v86, 0.15915494, v86
	v_pk_mul_f32 v[88:89], v[94:95], v[92:93]
	v_sin_f32_e32 v93, v86
	v_cos_f32_e32 v92, v86
	v_mov_b32_e32 v90, v87
	v_pk_mul_f32 v[86:87], v[4:5], v[90:91]
	v_add_f32_e32 v94, v88, v89
	v_pk_mul_f32 v[88:89], v[92:93], v[86:87]
	s_nop 0
	v_sub_f32_e32 v90, v88, v89
	v_mov_b32_e32 v88, v93
	v_mov_b32_e32 v89, v92
	v_pk_mul_f32 v[86:87], v[88:89], v[86:87]
	v_cvt_pk_bf16_f32 v88, v98, v96
	s_nop 0
	v_add_f32_e32 v89, v86, v87
	v_cvt_pk_bf16_f32 v86, v101, v99
	v_cvt_pk_bf16_f32 v87, v97, v90
	v_cvt_pk_bf16_f32 v89, v94, v89
	ds_write2_b64 v127, v[86:87], v[88:89] offset0:16 offset1:20
	s_waitcnt lgkmcnt(0)
	s_and_saveexec_b64 s[4:5], vcc
	s_cbranch_execz .LBB0_526
	v_or_b32_e32 v90, v178, v107
	v_mul_hi_i32 v91, v90, s90
	v_lshrrev_b32_e32 v92, 31, v91
	v_ashrrev_i32_e32 v91, 7, v91
	v_add_u32_e32 v91, v91, v92
	v_mul_i32_i24_e32 v92, 0x810, v91
	v_sub_u32_e32 v90, v90, v92
	v_lshl_or_b32 v91, v91, 3, s16
	v_mul_hi_i32_i24_e32 v93, 0x840, v91
	v_mul_i32_i24_e32 v92, 0x840, v91
	v_ashrrev_i32_e32 v91, 31, v90
	ds_read_b128 v[86:89], v173
	v_lshl_add_u64 v[90:91], v[92:93], 0, v[90:91]
	v_mad_u64_u32 v[94:95], s[8:9], v90, s91, v[108:109]
	v_mov_b32_e32 v90, v95
	v_mad_u64_u32 v[90:91], s[8:9], v91, s91, v[90:91]
	v_mov_b32_e32 v95, v90
	ds_read_b128 v[90:93], v174
	s_waitcnt lgkmcnt(1)
	global_store_dwordx4 v[94:95], v[86:89], off nt
	s_nop 1
	v_or_b32_e32 v86, v178, v170
	v_mul_hi_i32 v87, v86, s90
	v_lshrrev_b32_e32 v88, 31, v87
	v_ashrrev_i32_e32 v87, 7, v87
	v_add_u32_e32 v87, v87, v88
	v_mul_i32_i24_e32 v88, 0x810, v87
	v_sub_u32_e32 v86, v86, v88
	v_lshl_or_b32 v87, v87, 3, s16
	v_mul_hi_i32_i24_e32 v89, 0x840, v87
	v_mul_i32_i24_e32 v88, 0x840, v87
	v_ashrrev_i32_e32 v87, 31, v86
	v_lshl_add_u64 v[86:87], v[88:89], 0, v[86:87]
	v_mad_u64_u32 v[88:89], s[8:9], v86, s91, v[110:111]
	v_mov_b32_e32 v86, v89
	v_mad_u64_u32 v[86:87], s[8:9], v87, s91, v[86:87]
	v_mov_b32_e32 v89, v86
	s_waitcnt lgkmcnt(0)
	global_store_dwordx4 v[88:89], v[90:93], off nt
	ds_read_b128 v[86:89], v175
	s_nop 0
	v_or_b32_e32 v90, v178, v171
	v_mul_hi_i32 v91, v90, s90
	v_lshrrev_b32_e32 v92, 31, v91
	v_ashrrev_i32_e32 v91, 7, v91
	v_add_u32_e32 v91, v91, v92
	v_mul_i32_i24_e32 v92, 0x810, v91
	v_sub_u32_e32 v90, v90, v92
	v_lshl_or_b32 v91, v91, 3, s16
	v_mul_hi_i32_i24_e32 v93, 0x840, v91
	v_mul_i32_i24_e32 v92, 0x840, v91
	v_ashrrev_i32_e32 v91, 31, v90
	v_lshl_add_u64 v[90:91], v[92:93], 0, v[90:91]
	v_mad_u64_u32 v[92:93], s[8:9], v90, s91, v[112:113]
	v_mov_b32_e32 v90, v93
	v_mad_u64_u32 v[90:91], s[8:9], v91, s91, v[90:91]
	v_mov_b32_e32 v93, v90
	s_waitcnt lgkmcnt(0)
	global_store_dwordx4 v[92:93], v[86:89], off nt
